# GEMM compute segments: removed the adjacent s_setprio 0 / s_setprio 1 pair between MFMA 16 and 17 (two issue slots inside each MFMA-paced segment); per-phase priority flips unchanged
# speedup vs baseline: 1.0111x; 1.0004x over previous
; #define PG8_STAGE(bufoff, gbase, voff) do { _Pragma("unroll") for (int _i = 0; _i < 2; ++_i) \
;         __builtin_amdgcn_global_load_lds((const unsigned*)((const char*)(gbase) + (voff)[_i]), (LAS unsigned*)(lds + (bufoff) + ldsw + _i * 8192), 16, 0, 0); } while (0)
; #define PG8_LDA(dst, b, h) do { _Pragma("unroll") for (int m = 0; m < 4; ++m) _Pragma("unroll") for (int k = 0; k < 2; ++k) dst[m][k] = *(const LAS bf16x8*)(lds + PG8_SA(b, h) + aoff + m * 2048 + k * 1024); } while (0)
; #define PG8_LDB(dst, b, h) do { _Pragma("unroll") for (int n = 0; n < 2; ++n) _Pragma("unroll") for (int k = 0; k < 2; ++k) dst[n][k] = *(const LAS bf16x8*)(lds + PG8_SB(b, h) + boff + n * 2048 + k * 1024); } while (0)
; #define PG8_MMA(ai, bj, At, Bt) do { __builtin_amdgcn_s_setprio(1); _Pragma("unroll") for (int m = 0; m < 4; ++m) _Pragma("unroll") for (int n = 0; n < 2; ++n) _Pragma("unroll") for (int k = 0; k < 2; ++k) \
;         acc[ai][bj][m][n] = __builtin_amdgcn_mfma_f32_16x16x32_bf16(Bt[n][k], At[m][k], acc[ai][bj][m][n], 0, 0, 0); __builtin_amdgcn_s_setprio(0); } while (0)
; #define PG8_WAIT_V(n) asm volatile("s_waitcnt vmcnt(" #n ")" ::: "memory")
; #define PG8_WAIT_L(n) asm volatile("s_waitcnt lgkmcnt(" #n ")" ::: "memory")
; #define PG8_BAR __builtin_amdgcn_s_barrier()
; #define PG8_SCHED __builtin_amdgcn_sched_barrier(0)
; template <class Epi>
; DI void gemm_phase(LAS unsigned char* lds, const Gemm g, const StaticOrder S, const Epi E) {
;     ...
;         for (int t = 0; t < nt; t += 2) {
;             const bool last = (t == nt - 2);
;             const char* a1 = cA + (size_t)(t + 1) * kstep;
;             const char* a2 = last ? nA : cA + (size_t)(t + 2) * kstep; const char* b2 = last ? nB : cB + (size_t)(t + 2) * kstep;
;             const char* a3 = a2 + kstep; const char* b3 = b2 + kstep;
;             PG8_LDB(B0, 0, 0); PG8_LDB(B1, 0, 1); PG8_SCHED; PG8_LDA(At, 0, 0); PG8_STAGE(PG8_SA(1, 1), a1 + hstepA, voffA);
;             PG8_WAIT_V(8); PG8_WAIT_L(0); PG8_BAR; PG8_MMA(0, 0, At, B0); PG8_MMA(0, 1, At, B1); PG8_BAR; PG8_SCHED;
;             PG8_LDA(At, 0, 1); PG8_STAGE(PG8_SB(0, 0), b2, voffB); PG8_STAGE(PG8_SB(0, 1), b2 + hstepB, voffB); PG8_STAGE(PG8_SA(0, 0), a2, voffA);
;             PG8_WAIT_V(8); PG8_WAIT_L(0); PG8_BAR; PG8_MMA(1, 0, At, B0); PG8_MMA(1, 1, At, B1); PG8_BAR; PG8_SCHED;
.LBB0_241:
	s_add_u32 s20, s44, 0xfffc0080
	s_addc_u32 s21, s45, -1
	s_add_i32 s26, 0, 0x10000
	s_cmp_eq_u32 s79, 12
	s_cselect_b32 s61, s53, s21
	s_cselect_b32 s60, s52, s20
	s_cselect_b32 s31, s55, s51
	s_cselect_b32 s30, s54, s49
	s_add_u32 s98, s30, 0x80
	s_addc_u32 s99, s31, 0
	s_add_u32 s100, s60, 0x80
	s_addc_u32 s101, s61, 0
	s_add_i32 s27, 0, 0x14000
	v_add_u32_e32 v140, s26, v183
	v_add_u32_e32 v144, s27, v183
	ds_read_b128 v[128:131], v140
	ds_read_b128 v[132:135], v140 offset:1024
	ds_read_b128 v[136:139], v140 offset:2048
	ds_read_b128 v[140:143], v140 offset:3072
	ds_read_b128 v[170:173], v144
	ds_read_b128 v[174:177], v144 offset:1024
	ds_read_b128 v[178:181], v144 offset:2048
	ds_read_b128 v[186:189], v144 offset:3072
	s_add_i32 m0, s57, 0xc000
	ds_read_b128 v[190:193], v184
	ds_read_b128 v[194:197], v184 offset:1024
	ds_read_b128 v[220:223], v184 offset:2048
	ds_read_b128 v[230:233], v184 offset:3072
	ds_read_b128 v[234:237], v184 offset:4096
	ds_read_b128 v[238:241], v184 offset:5120
	ds_read_b128 v[242:245], v184 offset:6144
	ds_read_b128 v[246:249], v184 offset:7168
	global_load_lds_dwordx4 v166, s[44:45]
	s_add_i32 m0, s57, 0xe000
	s_nop 0
	global_load_lds_dwordx4 v168, s[44:45]
	s_waitcnt vmcnt(8)
	s_waitcnt lgkmcnt(0)
	s_barrier
	s_setprio 1
	s_waitcnt lgkmcnt(0)
	v_mfma_f32_16x16x32_bf16 v[124:127], v[128:131], v[190:193], v[124:127]
	v_mfma_f32_16x16x32_bf16 v[120:123], v[136:139], v[190:193], v[120:123]
	v_mfma_f32_16x16x32_bf16 v[108:111], v[128:131], v[220:223], v[108:111]
	v_mfma_f32_16x16x32_bf16 v[104:107], v[136:139], v[220:223], v[104:107]
	v_mfma_f32_16x16x32_bf16 v[92:95], v[128:131], v[234:237], v[92:95]
	v_mfma_f32_16x16x32_bf16 v[88:91], v[136:139], v[234:237], v[88:91]
	v_mfma_f32_16x16x32_bf16 v[76:79], v[128:131], v[242:245], v[76:79]
	v_mfma_f32_16x16x32_bf16 v[72:75], v[136:139], v[242:245], v[72:75]
	v_mfma_f32_16x16x32_bf16 v[124:127], v[132:135], v[194:197], v[124:127]
	v_mfma_f32_16x16x32_bf16 v[120:123], v[140:143], v[194:197], v[120:123]
	v_mfma_f32_16x16x32_bf16 v[108:111], v[132:135], v[230:233], v[108:111]
	v_mfma_f32_16x16x32_bf16 v[104:107], v[140:143], v[230:233], v[104:107]
	v_mfma_f32_16x16x32_bf16 v[92:95], v[132:135], v[238:241], v[92:95]
	v_mfma_f32_16x16x32_bf16 v[88:91], v[140:143], v[238:241], v[88:91]
	v_mfma_f32_16x16x32_bf16 v[76:79], v[132:135], v[246:249], v[76:79]
	v_mfma_f32_16x16x32_bf16 v[72:75], v[140:143], v[246:249], v[72:75]
	v_mfma_f32_16x16x32_bf16 v[116:119], v[170:173], v[190:193], v[116:119]
	v_mfma_f32_16x16x32_bf16 v[112:115], v[178:181], v[190:193], v[112:115]
	v_mfma_f32_16x16x32_bf16 v[100:103], v[170:173], v[220:223], v[100:103]
	v_mfma_f32_16x16x32_bf16 v[96:99], v[178:181], v[220:223], v[96:99]
	v_mfma_f32_16x16x32_bf16 v[84:87], v[170:173], v[234:237], v[84:87]
	v_mfma_f32_16x16x32_bf16 v[80:83], v[178:181], v[234:237], v[80:83]
	v_mfma_f32_16x16x32_bf16 v[68:71], v[170:173], v[242:245], v[68:71]
	v_mfma_f32_16x16x32_bf16 v[64:67], v[178:181], v[242:245], v[64:67]
	v_mfma_f32_16x16x32_bf16 v[116:119], v[174:177], v[194:197], v[116:119]
	v_mfma_f32_16x16x32_bf16 v[112:115], v[186:189], v[194:197], v[112:115]
	v_mfma_f32_16x16x32_bf16 v[100:103], v[174:177], v[230:233], v[100:103]
	v_mfma_f32_16x16x32_bf16 v[96:99], v[186:189], v[230:233], v[96:99]
	v_mfma_f32_16x16x32_bf16 v[84:87], v[174:177], v[238:241], v[84:87]
	v_mfma_f32_16x16x32_bf16 v[80:83], v[186:189], v[238:241], v[80:83]
	v_mfma_f32_16x16x32_bf16 v[68:71], v[174:177], v[246:249], v[68:71]
	v_mfma_f32_16x16x32_bf16 v[64:67], v[186:189], v[246:249], v[64:67]
	s_setprio 0
	s_barrier
	s_add_i32 s20, s26, s62
	s_mov_b32 m0, s20
	ds_read_b128 v[190:193], v184 offset:16384
	ds_read_b128 v[194:197], v184 offset:17408
	ds_read_b128 v[220:223], v184 offset:18432
	ds_read_b128 v[230:233], v184 offset:19456
	ds_read_b128 v[234:237], v184 offset:20480
	ds_read_b128 v[238:241], v184 offset:21504
	ds_read_b128 v[242:245], v184 offset:22528
	ds_read_b128 v[246:249], v184 offset:23552
	global_load_lds_dwordx4 v160, s[30:31]
	s_add_i32 m0, s20, 0x2000
	s_add_u32 s20, s30, 0x40000
	s_addc_u32 s21, s31, 0
	s_add_i32 s26, s27, s62
	global_load_lds_dwordx4 v164, s[30:31]
	s_mov_b32 m0, s26
	s_nop 0
	global_load_lds_dwordx4 v160, s[20:21]
	s_add_i32 m0, s26, 0x2000
	s_nop 0
	global_load_lds_dwordx4 v164, s[20:21]
	s_mov_b32 m0, s57
	s_nop 0
	global_load_lds_dwordx4 v158, s[60:61]
	s_mov_b32 m0, s59
	s_nop 0
	global_load_lds_dwordx4 v162, s[60:61]
	s_waitcnt vmcnt(8)
	s_waitcnt lgkmcnt(0)
	s_barrier
	s_setprio 1
	s_waitcnt lgkmcnt(0)
	v_mfma_f32_16x16x32_bf16 v[60:63], v[128:131], v[190:193], v[60:63]
	v_mfma_f32_16x16x32_bf16 v[56:59], v[136:139], v[190:193], v[56:59]
	v_mfma_f32_16x16x32_bf16 v[44:47], v[128:131], v[220:223], v[44:47]
	v_mfma_f32_16x16x32_bf16 v[40:43], v[136:139], v[220:223], v[40:43]
	v_mfma_f32_16x16x32_bf16 v[28:31], v[128:131], v[234:237], v[28:31]
	v_mfma_f32_16x16x32_bf16 v[24:27], v[136:139], v[234:237], v[24:27]
	v_mfma_f32_16x16x32_bf16 v[12:15], v[128:131], v[242:245], v[12:15]
	v_mfma_f32_16x16x32_bf16 v[8:11], v[136:139], v[242:245], v[8:11]
	v_mfma_f32_16x16x32_bf16 v[60:63], v[132:135], v[194:197], v[60:63]
	v_mfma_f32_16x16x32_bf16 v[56:59], v[140:143], v[194:197], v[56:59]
	v_mfma_f32_16x16x32_bf16 v[44:47], v[132:135], v[230:233], v[44:47]
	v_mfma_f32_16x16x32_bf16 v[40:43], v[140:143], v[230:233], v[40:43]
	v_mfma_f32_16x16x32_bf16 v[28:31], v[132:135], v[238:241], v[28:31]
	v_mfma_f32_16x16x32_bf16 v[24:27], v[140:143], v[238:241], v[24:27]
	v_mfma_f32_16x16x32_bf16 v[12:15], v[132:135], v[246:249], v[12:15]
	v_mfma_f32_16x16x32_bf16 v[8:11], v[140:143], v[246:249], v[8:11]
	v_mfma_f32_16x16x32_bf16 v[52:55], v[170:173], v[190:193], v[52:55]
	v_mfma_f32_16x16x32_bf16 v[48:51], v[178:181], v[190:193], v[48:51]
	v_mfma_f32_16x16x32_bf16 v[36:39], v[170:173], v[220:223], v[36:39]
	v_mfma_f32_16x16x32_bf16 v[32:35], v[178:181], v[220:223], v[32:35]
	v_mfma_f32_16x16x32_bf16 v[20:23], v[170:173], v[234:237], v[20:23]
	v_mfma_f32_16x16x32_bf16 v[16:19], v[178:181], v[234:237], v[16:19]
	v_mfma_f32_16x16x32_bf16 v[4:7], v[170:173], v[242:245], v[4:7]
	v_mfma_f32_16x16x32_bf16 v[0:3], v[178:181], v[242:245], v[0:3]
	v_mfma_f32_16x16x32_bf16 v[52:55], v[174:177], v[194:197], v[52:55]
	v_mfma_f32_16x16x32_bf16 v[48:51], v[186:189], v[194:197], v[48:51]
	v_mfma_f32_16x16x32_bf16 v[36:39], v[174:177], v[230:233], v[36:39]
	v_mfma_f32_16x16x32_bf16 v[32:35], v[186:189], v[230:233], v[32:35]
	v_mfma_f32_16x16x32_bf16 v[20:23], v[174:177], v[238:241], v[20:23]
	v_mfma_f32_16x16x32_bf16 v[16:19], v[186:189], v[238:241], v[16:19]
	v_mfma_f32_16x16x32_bf16 v[4:7], v[174:177], v[246:249], v[4:7]
	v_mfma_f32_16x16x32_bf16 v[0:3], v[186:189], v[246:249], v[0:3]
	s_setprio 0
	s_barrier
; #define PG8_STAGE(bufoff, gbase, voff) do { _Pragma("unroll") for (int _i = 0; _i < 2; ++_i) \
;         __builtin_amdgcn_global_load_lds((const unsigned*)((const char*)(gbase) + (voff)[_i]), (LAS unsigned*)(lds + (bufoff) + ldsw + _i * 8192), 16, 0, 0); } while (0)
; #define PG8_LDA(dst, b, h) do { _Pragma("unroll") for (int m = 0; m < 4; ++m) _Pragma("unroll") for (int k = 0; k < 2; ++k) dst[m][k] = *(const LAS bf16x8*)(lds + PG8_SA(b, h) + aoff + m * 2048 + k * 1024); } while (0)
; #define PG8_LDB(dst, b, h) do { _Pragma("unroll") for (int n = 0; n < 2; ++n) _Pragma("unroll") for (int k = 0; k < 2; ++k) dst[n][k] = *(const LAS bf16x8*)(lds + PG8_SB(b, h) + boff + n * 2048 + k * 1024); } while (0)
; #define PG8_MMA(ai, bj, At, Bt) do { __builtin_amdgcn_s_setprio(1); _Pragma("unroll") for (int m = 0; m < 4; ++m) _Pragma("unroll") for (int n = 0; n < 2; ++n) _Pragma("unroll") for (int k = 0; k < 2; ++k) \
;         acc[ai][bj][m][n] = __builtin_amdgcn_mfma_f32_16x16x32_bf16(Bt[n][k], At[m][k], acc[ai][bj][m][n], 0, 0, 0); __builtin_amdgcn_s_setprio(0); } while (0)
; #define PG8_WAIT_V(n) asm volatile("s_waitcnt vmcnt(" #n ")" ::: "memory")
; #define PG8_WAIT_L(n) asm volatile("s_waitcnt lgkmcnt(" #n ")" ::: "memory")
; #define PG8_BAR __builtin_amdgcn_s_barrier()
; #define PG8_SCHED __builtin_amdgcn_sched_barrier(0)
; template <class Epi>
; DI void gemm_phase(LAS unsigned char* lds, const Gemm g, const StaticOrder S, const Epi E) {
;     ...
;             PG8_LDB(B0, 1, 0); PG8_LDB(B1, 1, 1); PG8_SCHED; PG8_LDA(At, 1, 0); PG8_STAGE(PG8_SA(0, 1), a2 + hstepA, voffA);
;             PG8_WAIT_V(8); PG8_WAIT_L(0); PG8_BAR; PG8_MMA(0, 0, At, B0); PG8_MMA(0, 1, At, B1); PG8_BAR; PG8_SCHED;
;             PG8_LDA(At, 1, 1); PG8_STAGE(PG8_SB(1, 0), b3, voffB); PG8_STAGE(PG8_SB(1, 1), b3 + hstepB, voffB); PG8_STAGE(PG8_SA(1, 0), a3, voffA);
;             PG8_WAIT_V(8); PG8_WAIT_L(0); PG8_BAR; PG8_MMA(1, 0, At, B0); PG8_MMA(1, 1, At, B1); PG8_BAR; PG8_SCHED;
;         }
;         if (wr == 0) PG8_BAR;
	s_add_i32 s26, 0, 0x1c000
	v_add_u32_e32 v140, s74, v183
	v_add_u32_e32 v146, s26, v183
	ds_read_b128 v[128:131], v140
	ds_read_b128 v[132:135], v140 offset:1024
	ds_read_b128 v[136:139], v140 offset:2048
	ds_read_b128 v[140:143], v140 offset:3072
	ds_read_b128 v[170:173], v146
	ds_read_b128 v[174:177], v146 offset:1024
	ds_read_b128 v[178:181], v146 offset:2048
	ds_read_b128 v[186:189], v146 offset:3072
	s_add_u32 s20, s60, 0x40000
	s_addc_u32 s21, s61, 0
	s_mov_b32 m0, s68
	ds_read_b128 v[190:193], v184 offset:32768
	ds_read_b128 v[194:197], v184 offset:33792
	ds_read_b128 v[220:223], v184 offset:34816
	ds_read_b128 v[230:233], v184 offset:35840
	ds_read_b128 v[234:237], v184 offset:36864
	ds_read_b128 v[238:241], v184 offset:37888
	ds_read_b128 v[242:245], v184 offset:38912
	ds_read_b128 v[246:249], v184 offset:39936
	global_load_lds_dwordx4 v158, s[20:21]
	s_mov_b32 m0, s69
	s_nop 0
	global_load_lds_dwordx4 v162, s[20:21]
	s_waitcnt vmcnt(8)
	s_waitcnt lgkmcnt(0)
	s_barrier
	s_setprio 1
	s_waitcnt lgkmcnt(0)
	v_mfma_f32_16x16x32_bf16 v[124:127], v[128:131], v[190:193], v[124:127]
	v_mfma_f32_16x16x32_bf16 v[120:123], v[136:139], v[190:193], v[120:123]
	v_mfma_f32_16x16x32_bf16 v[108:111], v[128:131], v[220:223], v[108:111]
	v_mfma_f32_16x16x32_bf16 v[104:107], v[136:139], v[220:223], v[104:107]
	v_mfma_f32_16x16x32_bf16 v[92:95], v[128:131], v[234:237], v[92:95]
	v_mfma_f32_16x16x32_bf16 v[88:91], v[136:139], v[234:237], v[88:91]
	v_mfma_f32_16x16x32_bf16 v[76:79], v[128:131], v[242:245], v[76:79]
	v_mfma_f32_16x16x32_bf16 v[72:75], v[136:139], v[242:245], v[72:75]
	v_mfma_f32_16x16x32_bf16 v[124:127], v[132:135], v[194:197], v[124:127]
	v_mfma_f32_16x16x32_bf16 v[120:123], v[140:143], v[194:197], v[120:123]
	v_mfma_f32_16x16x32_bf16 v[108:111], v[132:135], v[230:233], v[108:111]
	v_mfma_f32_16x16x32_bf16 v[104:107], v[140:143], v[230:233], v[104:107]
	v_mfma_f32_16x16x32_bf16 v[92:95], v[132:135], v[238:241], v[92:95]
	v_mfma_f32_16x16x32_bf16 v[88:91], v[140:143], v[238:241], v[88:91]
	v_mfma_f32_16x16x32_bf16 v[76:79], v[132:135], v[246:249], v[76:79]
	v_mfma_f32_16x16x32_bf16 v[72:75], v[140:143], v[246:249], v[72:75]
	v_mfma_f32_16x16x32_bf16 v[116:119], v[170:173], v[190:193], v[116:119]
	v_mfma_f32_16x16x32_bf16 v[112:115], v[178:181], v[190:193], v[112:115]
	v_mfma_f32_16x16x32_bf16 v[100:103], v[170:173], v[220:223], v[100:103]
	v_mfma_f32_16x16x32_bf16 v[96:99], v[178:181], v[220:223], v[96:99]
	v_mfma_f32_16x16x32_bf16 v[84:87], v[170:173], v[234:237], v[84:87]
	v_mfma_f32_16x16x32_bf16 v[80:83], v[178:181], v[234:237], v[80:83]
	v_mfma_f32_16x16x32_bf16 v[68:71], v[170:173], v[242:245], v[68:71]
	v_mfma_f32_16x16x32_bf16 v[64:67], v[178:181], v[242:245], v[64:67]
	v_mfma_f32_16x16x32_bf16 v[116:119], v[174:177], v[194:197], v[116:119]
	v_mfma_f32_16x16x32_bf16 v[112:115], v[186:189], v[194:197], v[112:115]
	v_mfma_f32_16x16x32_bf16 v[100:103], v[174:177], v[230:233], v[100:103]
	v_mfma_f32_16x16x32_bf16 v[96:99], v[186:189], v[230:233], v[96:99]
	v_mfma_f32_16x16x32_bf16 v[84:87], v[174:177], v[238:241], v[84:87]
	v_mfma_f32_16x16x32_bf16 v[80:83], v[186:189], v[238:241], v[80:83]
	v_mfma_f32_16x16x32_bf16 v[68:71], v[174:177], v[246:249], v[68:71]
	v_mfma_f32_16x16x32_bf16 v[64:67], v[186:189], v[246:249], v[64:67]
	s_setprio 0
	s_barrier
	s_add_i32 s20, s74, s62
	s_mov_b32 m0, s20
	ds_read_b128 v[190:193], v184 offset:49152
	ds_read_b128 v[194:197], v184 offset:50176
	ds_read_b128 v[220:223], v184 offset:51200
	ds_read_b128 v[230:233], v184 offset:52224
	ds_read_b128 v[234:237], v184 offset:53248
	ds_read_b128 v[238:241], v184 offset:54272
	ds_read_b128 v[242:245], v184 offset:55296
	ds_read_b128 v[246:249], v184 offset:56320
	global_load_lds_dwordx4 v160, s[98:99]
	s_add_i32 m0, s20, 0x2000
	s_add_u32 s20, s30, 0x40080
	s_addc_u32 s21, s31, 0
	s_add_i32 s26, s26, s62
	global_load_lds_dwordx4 v164, s[98:99]
	s_mov_b32 m0, s26
	s_nop 0
	global_load_lds_dwordx4 v160, s[20:21]
	s_add_i32 m0, s26, 0x2000
	s_nop 0
	global_load_lds_dwordx4 v164, s[20:21]
	s_mov_b32 m0, s72
	s_nop 0
	global_load_lds_dwordx4 v158, s[100:101]
	s_mov_b32 m0, s73
	s_nop 0
	global_load_lds_dwordx4 v162, s[100:101]
	s_waitcnt vmcnt(8)
	s_waitcnt lgkmcnt(0)
	s_barrier
	s_setprio 1
	s_waitcnt lgkmcnt(0)
	v_mfma_f32_16x16x32_bf16 v[60:63], v[128:131], v[190:193], v[60:63]
	v_mfma_f32_16x16x32_bf16 v[56:59], v[136:139], v[190:193], v[56:59]
	v_mfma_f32_16x16x32_bf16 v[44:47], v[128:131], v[220:223], v[44:47]
	v_mfma_f32_16x16x32_bf16 v[40:43], v[136:139], v[220:223], v[40:43]
	v_mfma_f32_16x16x32_bf16 v[28:31], v[128:131], v[234:237], v[28:31]
	v_mfma_f32_16x16x32_bf16 v[24:27], v[136:139], v[234:237], v[24:27]
	v_mfma_f32_16x16x32_bf16 v[12:15], v[128:131], v[242:245], v[12:15]
	v_mfma_f32_16x16x32_bf16 v[8:11], v[136:139], v[242:245], v[8:11]
	v_mfma_f32_16x16x32_bf16 v[60:63], v[132:135], v[194:197], v[60:63]
	v_mfma_f32_16x16x32_bf16 v[56:59], v[140:143], v[194:197], v[56:59]
	v_mfma_f32_16x16x32_bf16 v[44:47], v[132:135], v[230:233], v[44:47]
	v_mfma_f32_16x16x32_bf16 v[40:43], v[140:143], v[230:233], v[40:43]
	v_mfma_f32_16x16x32_bf16 v[28:31], v[132:135], v[238:241], v[28:31]
	v_mfma_f32_16x16x32_bf16 v[24:27], v[140:143], v[238:241], v[24:27]
	v_mfma_f32_16x16x32_bf16 v[12:15], v[132:135], v[246:249], v[12:15]
	v_mfma_f32_16x16x32_bf16 v[8:11], v[140:143], v[246:249], v[8:11]
	v_mfma_f32_16x16x32_bf16 v[52:55], v[170:173], v[190:193], v[52:55]
	v_mfma_f32_16x16x32_bf16 v[48:51], v[178:181], v[190:193], v[48:51]
	v_mfma_f32_16x16x32_bf16 v[36:39], v[170:173], v[220:223], v[36:39]
	v_mfma_f32_16x16x32_bf16 v[32:35], v[178:181], v[220:223], v[32:35]
	v_mfma_f32_16x16x32_bf16 v[20:23], v[170:173], v[234:237], v[20:23]
	v_mfma_f32_16x16x32_bf16 v[16:19], v[178:181], v[234:237], v[16:19]
	v_mfma_f32_16x16x32_bf16 v[4:7], v[170:173], v[242:245], v[4:7]
	v_mfma_f32_16x16x32_bf16 v[0:3], v[178:181], v[242:245], v[0:3]
	v_mfma_f32_16x16x32_bf16 v[52:55], v[174:177], v[194:197], v[52:55]
	v_mfma_f32_16x16x32_bf16 v[48:51], v[186:189], v[194:197], v[48:51]
	v_mfma_f32_16x16x32_bf16 v[36:39], v[174:177], v[230:233], v[36:39]
	v_mfma_f32_16x16x32_bf16 v[32:35], v[186:189], v[230:233], v[32:35]
	v_mfma_f32_16x16x32_bf16 v[20:23], v[174:177], v[238:241], v[20:23]
	v_mfma_f32_16x16x32_bf16 v[16:19], v[186:189], v[238:241], v[16:19]
	v_mfma_f32_16x16x32_bf16 v[4:7], v[174:177], v[246:249], v[4:7]
	v_mfma_f32_16x16x32_bf16 v[0:3], v[186:189], v[246:249], v[0:3]
	s_setprio 0
	s_barrier
	s_add_i32 s79, s79, 2
	s_add_u32 s44, s44, 0x100
	s_addc_u32 s45, s45, 0
	s_add_u32 s49, s49, 0x100
	s_addc_u32 s51, s51, 0
	s_cmp_gt_u32 s79, 13
	s_cbranch_scc0 .LBB0_241
	s_and_b64 vcc, exec, s[46:47]
	s_cbranch_vccz .LBB0_244
	s_barrier

; #define PG8_STAGE(bufoff, gbase, voff) do { _Pragma("unroll") for (int _i = 0; _i < 2; ++_i) \
;         __builtin_amdgcn_global_load_lds((const unsigned*)((const char*)(gbase) + (voff)[_i]), (LAS unsigned*)(lds + (bufoff) + ldsw + _i * 8192), 16, 0, 0); } while (0)
; #define PG8_LDA(dst, b, h) do { _Pragma("unroll") for (int m = 0; m < 4; ++m) _Pragma("unroll") for (int k = 0; k < 2; ++k) dst[m][k] = *(const LAS bf16x8*)(lds + PG8_SA(b, h) + aoff + m * 2048 + k * 1024); } while (0)
; #define PG8_LDB(dst, b, h) do { _Pragma("unroll") for (int n = 0; n < 2; ++n) _Pragma("unroll") for (int k = 0; k < 2; ++k) dst[n][k] = *(const LAS bf16x8*)(lds + PG8_SB(b, h) + boff + n * 2048 + k * 1024); } while (0)
; #define PG8_MMA(ai, bj, At, Bt) do { __builtin_amdgcn_s_setprio(1); _Pragma("unroll") for (int m = 0; m < 4; ++m) _Pragma("unroll") for (int n = 0; n < 2; ++n) _Pragma("unroll") for (int k = 0; k < 2; ++k) \
;         acc[ai][bj][m][n] = __builtin_amdgcn_mfma_f32_16x16x32_bf16(Bt[n][k], At[m][k], acc[ai][bj][m][n], 0, 0, 0); __builtin_amdgcn_s_setprio(0); } while (0)
; #define PG8_WAIT_V(n) asm volatile("s_waitcnt vmcnt(" #n ")" ::: "memory")
; #define PG8_WAIT_L(n) asm volatile("s_waitcnt lgkmcnt(" #n ")" ::: "memory")
; #define PG8_BAR __builtin_amdgcn_s_barrier()
; #define PG8_SCHED __builtin_amdgcn_sched_barrier(0)
; template <class Epi>
; DI void gemm_phase(LAS unsigned char* lds, const Gemm g, const StaticOrder S, const Epi E) {
;     ...
;         for (int t = 0; t < nt; t += 2) {
;             const bool last = (t == nt - 2);
;             const char* a1 = cA + (size_t)(t + 1) * kstep;
;             const char* a2 = last ? nA : cA + (size_t)(t + 2) * kstep; const char* b2 = last ? nB : cB + (size_t)(t + 2) * kstep;
;             const char* a3 = a2 + kstep; const char* b3 = b2 + kstep;
;             PG8_LDB(B0, 0, 0); PG8_LDB(B1, 0, 1); PG8_SCHED; PG8_LDA(At, 0, 0); PG8_STAGE(PG8_SA(1, 1), a1 + hstepA, voffA);
;             PG8_WAIT_V(8); PG8_WAIT_L(0); PG8_BAR; PG8_MMA(0, 0, At, B0); PG8_MMA(0, 1, At, B1); PG8_BAR; PG8_SCHED;
;             PG8_LDA(At, 0, 1); PG8_STAGE(PG8_SB(0, 0), b2, voffB); PG8_STAGE(PG8_SB(0, 1), b2 + hstepB, voffB); PG8_STAGE(PG8_SA(0, 0), a2, voffA);
;             PG8_WAIT_V(8); PG8_WAIT_L(0); PG8_BAR; PG8_MMA(1, 0, At, B0); PG8_MMA(1, 1, At, B1); PG8_BAR; PG8_SCHED;
.LBB0_290:
	s_add_u32 s20, s54, 0xfffc0080
	s_addc_u32 s21, s55, -1
	s_add_i32 s26, 0, 0x10000
	s_cmp_eq_u32 s72, 12
	s_cselect_b32 s57, s43, s21
	s_cselect_b32 s56, s42, s20
	v_add_u32_e32 v140, s26, v145
	s_cselect_b32 s31, s51, s47
	s_cselect_b32 s30, s50, s45
	s_add_u32 s98, s30, 0x80
	s_addc_u32 s99, s31, 0
	s_add_u32 s100, s56, 0x80
	s_addc_u32 s101, s57, 0
	s_add_i32 s27, 0, 0x14000
	ds_read_b128 v[158:161], v140
	ds_read_b128 v[162:165], v140 offset:1024
	ds_read_b128 v[166:169], v140 offset:2048
	ds_read_b128 v[170:173], v140 offset:3072
	v_add_u32_e32 v140, s27, v145
	ds_read_b128 v[174:177], v140
	ds_read_b128 v[178:181], v140 offset:1024
	ds_read_b128 v[182:185], v140 offset:2048
	ds_read_b128 v[186:189], v140 offset:3072
	s_add_i32 m0, s49, 0xc000
	ds_read_b128 v[190:193], v157
	ds_read_b128 v[194:197], v157 offset:1024
	ds_read_b128 v[220:223], v157 offset:2048
	ds_read_b128 v[230:233], v157 offset:3072
	ds_read_b128 v[234:237], v157 offset:4096
	ds_read_b128 v[238:241], v157 offset:5120
	ds_read_b128 v[242:245], v157 offset:6144
	ds_read_b128 v[246:249], v157 offset:7168
	global_load_lds_dwordx4 v136, s[54:55]
	s_add_i32 m0, s49, 0xe000
	s_nop 0
	global_load_lds_dwordx4 v138, s[54:55]
	s_waitcnt vmcnt(8)
	s_waitcnt lgkmcnt(0)
	s_barrier
	s_setprio 1
	s_waitcnt lgkmcnt(0)
	v_mfma_f32_16x16x32_bf16 v[124:127], v[158:161], v[190:193], v[124:127]
	v_mfma_f32_16x16x32_bf16 v[120:123], v[166:169], v[190:193], v[120:123]
	v_mfma_f32_16x16x32_bf16 v[116:119], v[158:161], v[220:223], v[116:119]
	v_mfma_f32_16x16x32_bf16 v[108:111], v[166:169], v[220:223], v[108:111]
	v_mfma_f32_16x16x32_bf16 v[100:103], v[158:161], v[234:237], v[100:103]
	v_mfma_f32_16x16x32_bf16 v[92:95], v[166:169], v[234:237], v[92:95]
	v_mfma_f32_16x16x32_bf16 v[84:87], v[158:161], v[242:245], v[84:87]
	v_mfma_f32_16x16x32_bf16 v[76:79], v[166:169], v[242:245], v[76:79]
	v_mfma_f32_16x16x32_bf16 v[124:127], v[162:165], v[194:197], v[124:127]
	v_mfma_f32_16x16x32_bf16 v[120:123], v[170:173], v[194:197], v[120:123]
	v_mfma_f32_16x16x32_bf16 v[116:119], v[162:165], v[230:233], v[116:119]
	v_mfma_f32_16x16x32_bf16 v[108:111], v[170:173], v[230:233], v[108:111]
	v_mfma_f32_16x16x32_bf16 v[100:103], v[162:165], v[238:241], v[100:103]
	v_mfma_f32_16x16x32_bf16 v[92:95], v[170:173], v[238:241], v[92:95]
	v_mfma_f32_16x16x32_bf16 v[84:87], v[162:165], v[246:249], v[84:87]
	v_mfma_f32_16x16x32_bf16 v[76:79], v[170:173], v[246:249], v[76:79]
	v_mfma_f32_16x16x32_bf16 v[112:115], v[174:177], v[190:193], v[112:115]
	v_mfma_f32_16x16x32_bf16 v[104:107], v[182:185], v[190:193], v[104:107]
	v_mfma_f32_16x16x32_bf16 v[96:99], v[174:177], v[220:223], v[96:99]
	v_mfma_f32_16x16x32_bf16 v[88:91], v[182:185], v[220:223], v[88:91]
	v_mfma_f32_16x16x32_bf16 v[80:83], v[174:177], v[234:237], v[80:83]
	v_mfma_f32_16x16x32_bf16 v[72:75], v[182:185], v[234:237], v[72:75]
	v_mfma_f32_16x16x32_bf16 v[68:71], v[174:177], v[242:245], v[68:71]
	v_mfma_f32_16x16x32_bf16 v[64:67], v[182:185], v[242:245], v[64:67]
	v_mfma_f32_16x16x32_bf16 v[112:115], v[178:181], v[194:197], v[112:115]
	v_mfma_f32_16x16x32_bf16 v[104:107], v[186:189], v[194:197], v[104:107]
	v_mfma_f32_16x16x32_bf16 v[96:99], v[178:181], v[230:233], v[96:99]
	v_mfma_f32_16x16x32_bf16 v[88:91], v[186:189], v[230:233], v[88:91]
	v_mfma_f32_16x16x32_bf16 v[80:83], v[178:181], v[238:241], v[80:83]
	v_mfma_f32_16x16x32_bf16 v[72:75], v[186:189], v[238:241], v[72:75]
	v_mfma_f32_16x16x32_bf16 v[68:71], v[178:181], v[246:249], v[68:71]
	v_mfma_f32_16x16x32_bf16 v[64:67], v[186:189], v[246:249], v[64:67]
	s_setprio 0
	s_barrier
	s_add_i32 s20, s26, s58
	s_mov_b32 m0, s20
	ds_read_b128 v[190:193], v157 offset:16384
	ds_read_b128 v[194:197], v157 offset:17408
	ds_read_b128 v[220:223], v157 offset:18432
	ds_read_b128 v[230:233], v157 offset:19456
	ds_read_b128 v[234:237], v157 offset:20480
	ds_read_b128 v[238:241], v157 offset:21504
	ds_read_b128 v[242:245], v157 offset:22528
	ds_read_b128 v[246:249], v157 offset:23552
	global_load_lds_dwordx4 v130, s[30:31]
	s_add_i32 m0, s20, 0x2000
	s_add_u32 s20, s30, 0x40000
	s_addc_u32 s21, s31, 0
	s_add_i32 s26, s27, s58
	global_load_lds_dwordx4 v134, s[30:31]
	s_mov_b32 m0, s26
	s_nop 0
	global_load_lds_dwordx4 v130, s[20:21]
	s_add_i32 m0, s26, 0x2000
	s_nop 0
	global_load_lds_dwordx4 v134, s[20:21]
	s_mov_b32 m0, s49
	s_nop 0
	global_load_lds_dwordx4 v128, s[56:57]
	s_mov_b32 m0, s53
	s_nop 0
	global_load_lds_dwordx4 v132, s[56:57]
	s_waitcnt vmcnt(8)
	s_waitcnt lgkmcnt(0)
	s_barrier
	s_setprio 1
	s_waitcnt lgkmcnt(0)
	v_mfma_f32_16x16x32_bf16 v[60:63], v[158:161], v[190:193], v[60:63]
	v_mfma_f32_16x16x32_bf16 v[56:59], v[166:169], v[190:193], v[56:59]
	v_mfma_f32_16x16x32_bf16 v[52:55], v[158:161], v[220:223], v[52:55]
	v_mfma_f32_16x16x32_bf16 v[44:47], v[166:169], v[220:223], v[44:47]
	v_mfma_f32_16x16x32_bf16 v[36:39], v[158:161], v[234:237], v[36:39]
	v_mfma_f32_16x16x32_bf16 v[28:31], v[166:169], v[234:237], v[28:31]
	v_mfma_f32_16x16x32_bf16 v[20:23], v[158:161], v[242:245], v[20:23]
	v_mfma_f32_16x16x32_bf16 v[12:15], v[166:169], v[242:245], v[12:15]
	v_mfma_f32_16x16x32_bf16 v[60:63], v[162:165], v[194:197], v[60:63]
	v_mfma_f32_16x16x32_bf16 v[56:59], v[170:173], v[194:197], v[56:59]
	v_mfma_f32_16x16x32_bf16 v[52:55], v[162:165], v[230:233], v[52:55]
	v_mfma_f32_16x16x32_bf16 v[44:47], v[170:173], v[230:233], v[44:47]
	v_mfma_f32_16x16x32_bf16 v[36:39], v[162:165], v[238:241], v[36:39]
	v_mfma_f32_16x16x32_bf16 v[28:31], v[170:173], v[238:241], v[28:31]
	v_mfma_f32_16x16x32_bf16 v[20:23], v[162:165], v[246:249], v[20:23]
	v_mfma_f32_16x16x32_bf16 v[12:15], v[170:173], v[246:249], v[12:15]
	v_mfma_f32_16x16x32_bf16 v[48:51], v[174:177], v[190:193], v[48:51]
	v_mfma_f32_16x16x32_bf16 v[40:43], v[182:185], v[190:193], v[40:43]
	v_mfma_f32_16x16x32_bf16 v[32:35], v[174:177], v[220:223], v[32:35]
	v_mfma_f32_16x16x32_bf16 v[24:27], v[182:185], v[220:223], v[24:27]
	v_mfma_f32_16x16x32_bf16 v[16:19], v[174:177], v[234:237], v[16:19]
	v_mfma_f32_16x16x32_bf16 v[8:11], v[182:185], v[234:237], v[8:11]
	v_mfma_f32_16x16x32_bf16 v[4:7], v[174:177], v[242:245], v[4:7]
	v_mfma_f32_16x16x32_bf16 v[0:3], v[182:185], v[242:245], v[0:3]
	v_mfma_f32_16x16x32_bf16 v[48:51], v[178:181], v[194:197], v[48:51]
	v_mfma_f32_16x16x32_bf16 v[40:43], v[186:189], v[194:197], v[40:43]
	v_mfma_f32_16x16x32_bf16 v[32:35], v[178:181], v[230:233], v[32:35]
	v_mfma_f32_16x16x32_bf16 v[24:27], v[186:189], v[230:233], v[24:27]
	v_mfma_f32_16x16x32_bf16 v[16:19], v[178:181], v[238:241], v[16:19]
	v_mfma_f32_16x16x32_bf16 v[8:11], v[186:189], v[238:241], v[8:11]
	v_mfma_f32_16x16x32_bf16 v[4:7], v[178:181], v[246:249], v[4:7]
	v_mfma_f32_16x16x32_bf16 v[0:3], v[186:189], v[246:249], v[0:3]
	s_setprio 0
	s_barrier
; #define PG8_STAGE(bufoff, gbase, voff) do { _Pragma("unroll") for (int _i = 0; _i < 2; ++_i) \
;         __builtin_amdgcn_global_load_lds((const unsigned*)((const char*)(gbase) + (voff)[_i]), (LAS unsigned*)(lds + (bufoff) + ldsw + _i * 8192), 16, 0, 0); } while (0)
; #define PG8_LDA(dst, b, h) do { _Pragma("unroll") for (int m = 0; m < 4; ++m) _Pragma("unroll") for (int k = 0; k < 2; ++k) dst[m][k] = *(const LAS bf16x8*)(lds + PG8_SA(b, h) + aoff + m * 2048 + k * 1024); } while (0)
; #define PG8_LDB(dst, b, h) do { _Pragma("unroll") for (int n = 0; n < 2; ++n) _Pragma("unroll") for (int k = 0; k < 2; ++k) dst[n][k] = *(const LAS bf16x8*)(lds + PG8_SB(b, h) + boff + n * 2048 + k * 1024); } while (0)
; #define PG8_MMA(ai, bj, At, Bt) do { __builtin_amdgcn_s_setprio(1); _Pragma("unroll") for (int m = 0; m < 4; ++m) _Pragma("unroll") for (int n = 0; n < 2; ++n) _Pragma("unroll") for (int k = 0; k < 2; ++k) \
;         acc[ai][bj][m][n] = __builtin_amdgcn_mfma_f32_16x16x32_bf16(Bt[n][k], At[m][k], acc[ai][bj][m][n], 0, 0, 0); __builtin_amdgcn_s_setprio(0); } while (0)
; #define PG8_WAIT_V(n) asm volatile("s_waitcnt vmcnt(" #n ")" ::: "memory")
; #define PG8_WAIT_L(n) asm volatile("s_waitcnt lgkmcnt(" #n ")" ::: "memory")
; #define PG8_BAR __builtin_amdgcn_s_barrier()
; #define PG8_SCHED __builtin_amdgcn_sched_barrier(0)
; template <class Epi>
; DI void gemm_phase(LAS unsigned char* lds, const Gemm g, const StaticOrder S, const Epi E) {
;     ...
;             PG8_LDB(B0, 1, 0); PG8_LDB(B1, 1, 1); PG8_SCHED; PG8_LDA(At, 1, 0); PG8_STAGE(PG8_SA(0, 1), a2 + hstepA, voffA);
;             PG8_WAIT_V(8); PG8_WAIT_L(0); PG8_BAR; PG8_MMA(0, 0, At, B0); PG8_MMA(0, 1, At, B1); PG8_BAR; PG8_SCHED;
;             PG8_LDA(At, 1, 1); PG8_STAGE(PG8_SB(1, 0), b3, voffB); PG8_STAGE(PG8_SB(1, 1), b3 + hstepB, voffB); PG8_STAGE(PG8_SA(1, 0), a3, voffA);
;             PG8_WAIT_V(8); PG8_WAIT_L(0); PG8_BAR; PG8_MMA(1, 0, At, B0); PG8_MMA(1, 1, At, B1); PG8_BAR; PG8_SCHED;
;         }
;         if (wr == 0) PG8_BAR;
	v_add_u32_e32 v140, s74, v145
	s_add_i32 s26, 0, 0x1c000
	ds_read_b128 v[158:161], v140
	ds_read_b128 v[162:165], v140 offset:1024
	ds_read_b128 v[166:169], v140 offset:2048
	ds_read_b128 v[170:173], v140 offset:3072
	v_add_u32_e32 v140, s26, v145
	ds_read_b128 v[174:177], v140
	ds_read_b128 v[178:181], v140 offset:1024
	ds_read_b128 v[182:185], v140 offset:2048
	ds_read_b128 v[186:189], v140 offset:3072
	s_add_u32 s20, s56, 0x40000
	s_addc_u32 s21, s57, 0
	s_mov_b32 m0, s59
	ds_read_b128 v[190:193], v157 offset:32768
	ds_read_b128 v[194:197], v157 offset:33792
	ds_read_b128 v[220:223], v157 offset:34816
	ds_read_b128 v[230:233], v157 offset:35840
	ds_read_b128 v[234:237], v157 offset:36864
	ds_read_b128 v[238:241], v157 offset:37888
	ds_read_b128 v[242:245], v157 offset:38912
	ds_read_b128 v[246:249], v157 offset:39936
	global_load_lds_dwordx4 v128, s[20:21]
	s_mov_b32 m0, s60
	s_nop 0
	global_load_lds_dwordx4 v132, s[20:21]
	s_waitcnt vmcnt(8)
	s_waitcnt lgkmcnt(0)
	s_barrier
	s_setprio 1
	s_waitcnt lgkmcnt(0)
	v_mfma_f32_16x16x32_bf16 v[124:127], v[158:161], v[190:193], v[124:127]
	v_mfma_f32_16x16x32_bf16 v[120:123], v[166:169], v[190:193], v[120:123]
	v_mfma_f32_16x16x32_bf16 v[116:119], v[158:161], v[220:223], v[116:119]
	v_mfma_f32_16x16x32_bf16 v[108:111], v[166:169], v[220:223], v[108:111]
	v_mfma_f32_16x16x32_bf16 v[100:103], v[158:161], v[234:237], v[100:103]
	v_mfma_f32_16x16x32_bf16 v[92:95], v[166:169], v[234:237], v[92:95]
	v_mfma_f32_16x16x32_bf16 v[84:87], v[158:161], v[242:245], v[84:87]
	v_mfma_f32_16x16x32_bf16 v[76:79], v[166:169], v[242:245], v[76:79]
	v_mfma_f32_16x16x32_bf16 v[124:127], v[162:165], v[194:197], v[124:127]
	v_mfma_f32_16x16x32_bf16 v[120:123], v[170:173], v[194:197], v[120:123]
	v_mfma_f32_16x16x32_bf16 v[116:119], v[162:165], v[230:233], v[116:119]
	v_mfma_f32_16x16x32_bf16 v[108:111], v[170:173], v[230:233], v[108:111]
	v_mfma_f32_16x16x32_bf16 v[100:103], v[162:165], v[238:241], v[100:103]
	v_mfma_f32_16x16x32_bf16 v[92:95], v[170:173], v[238:241], v[92:95]
	v_mfma_f32_16x16x32_bf16 v[84:87], v[162:165], v[246:249], v[84:87]
	v_mfma_f32_16x16x32_bf16 v[76:79], v[170:173], v[246:249], v[76:79]
	v_mfma_f32_16x16x32_bf16 v[112:115], v[174:177], v[190:193], v[112:115]
	v_mfma_f32_16x16x32_bf16 v[104:107], v[182:185], v[190:193], v[104:107]
	v_mfma_f32_16x16x32_bf16 v[96:99], v[174:177], v[220:223], v[96:99]
	v_mfma_f32_16x16x32_bf16 v[88:91], v[182:185], v[220:223], v[88:91]
	v_mfma_f32_16x16x32_bf16 v[80:83], v[174:177], v[234:237], v[80:83]
	v_mfma_f32_16x16x32_bf16 v[72:75], v[182:185], v[234:237], v[72:75]
	v_mfma_f32_16x16x32_bf16 v[68:71], v[174:177], v[242:245], v[68:71]
	v_mfma_f32_16x16x32_bf16 v[64:67], v[182:185], v[242:245], v[64:67]
	v_mfma_f32_16x16x32_bf16 v[112:115], v[178:181], v[194:197], v[112:115]
	v_mfma_f32_16x16x32_bf16 v[104:107], v[186:189], v[194:197], v[104:107]
	v_mfma_f32_16x16x32_bf16 v[96:99], v[178:181], v[230:233], v[96:99]
	v_mfma_f32_16x16x32_bf16 v[88:91], v[186:189], v[230:233], v[88:91]
	v_mfma_f32_16x16x32_bf16 v[80:83], v[178:181], v[238:241], v[80:83]
	v_mfma_f32_16x16x32_bf16 v[72:75], v[186:189], v[238:241], v[72:75]
	v_mfma_f32_16x16x32_bf16 v[68:71], v[178:181], v[246:249], v[68:71]
	v_mfma_f32_16x16x32_bf16 v[64:67], v[186:189], v[246:249], v[64:67]
	s_setprio 0
	s_barrier
	s_add_i32 s20, s74, s58
	s_mov_b32 m0, s20
	ds_read_b128 v[190:193], v157 offset:49152
	ds_read_b128 v[194:197], v157 offset:50176
	ds_read_b128 v[220:223], v157 offset:51200
	ds_read_b128 v[230:233], v157 offset:52224
	ds_read_b128 v[234:237], v157 offset:53248
	ds_read_b128 v[238:241], v157 offset:54272
	ds_read_b128 v[242:245], v157 offset:55296
	ds_read_b128 v[246:249], v157 offset:56320
	global_load_lds_dwordx4 v130, s[98:99]
	s_add_i32 m0, s20, 0x2000
	s_add_u32 s20, s30, 0x40080
	s_addc_u32 s21, s31, 0
	s_add_i32 s26, s26, s58
	global_load_lds_dwordx4 v134, s[98:99]
	s_mov_b32 m0, s26
	s_nop 0
	global_load_lds_dwordx4 v130, s[20:21]
	s_add_i32 m0, s26, 0x2000
	s_nop 0
	global_load_lds_dwordx4 v134, s[20:21]
	s_mov_b32 m0, s68
	s_nop 0
	global_load_lds_dwordx4 v128, s[100:101]
	s_mov_b32 m0, s69
	s_nop 0
	global_load_lds_dwordx4 v132, s[100:101]
	s_waitcnt vmcnt(8)
	s_waitcnt lgkmcnt(0)
	s_barrier
	s_setprio 1
	s_waitcnt lgkmcnt(0)
	v_mfma_f32_16x16x32_bf16 v[60:63], v[158:161], v[190:193], v[60:63]
	v_mfma_f32_16x16x32_bf16 v[56:59], v[166:169], v[190:193], v[56:59]
	v_mfma_f32_16x16x32_bf16 v[52:55], v[158:161], v[220:223], v[52:55]
	v_mfma_f32_16x16x32_bf16 v[44:47], v[166:169], v[220:223], v[44:47]
	v_mfma_f32_16x16x32_bf16 v[36:39], v[158:161], v[234:237], v[36:39]
	v_mfma_f32_16x16x32_bf16 v[28:31], v[166:169], v[234:237], v[28:31]
	v_mfma_f32_16x16x32_bf16 v[20:23], v[158:161], v[242:245], v[20:23]
	v_mfma_f32_16x16x32_bf16 v[12:15], v[166:169], v[242:245], v[12:15]
	v_mfma_f32_16x16x32_bf16 v[60:63], v[162:165], v[194:197], v[60:63]
	v_mfma_f32_16x16x32_bf16 v[56:59], v[170:173], v[194:197], v[56:59]
	v_mfma_f32_16x16x32_bf16 v[52:55], v[162:165], v[230:233], v[52:55]
	v_mfma_f32_16x16x32_bf16 v[44:47], v[170:173], v[230:233], v[44:47]
	v_mfma_f32_16x16x32_bf16 v[36:39], v[162:165], v[238:241], v[36:39]
	v_mfma_f32_16x16x32_bf16 v[28:31], v[170:173], v[238:241], v[28:31]
	v_mfma_f32_16x16x32_bf16 v[20:23], v[162:165], v[246:249], v[20:23]
	v_mfma_f32_16x16x32_bf16 v[12:15], v[170:173], v[246:249], v[12:15]
	v_mfma_f32_16x16x32_bf16 v[48:51], v[174:177], v[190:193], v[48:51]
	v_mfma_f32_16x16x32_bf16 v[40:43], v[182:185], v[190:193], v[40:43]
	v_mfma_f32_16x16x32_bf16 v[32:35], v[174:177], v[220:223], v[32:35]
	v_mfma_f32_16x16x32_bf16 v[24:27], v[182:185], v[220:223], v[24:27]
	v_mfma_f32_16x16x32_bf16 v[16:19], v[174:177], v[234:237], v[16:19]
	v_mfma_f32_16x16x32_bf16 v[8:11], v[182:185], v[234:237], v[8:11]
	v_mfma_f32_16x16x32_bf16 v[4:7], v[174:177], v[242:245], v[4:7]
	v_mfma_f32_16x16x32_bf16 v[0:3], v[182:185], v[242:245], v[0:3]
	v_mfma_f32_16x16x32_bf16 v[48:51], v[178:181], v[194:197], v[48:51]
	v_mfma_f32_16x16x32_bf16 v[40:43], v[186:189], v[194:197], v[40:43]
	v_mfma_f32_16x16x32_bf16 v[32:35], v[178:181], v[230:233], v[32:35]
	v_mfma_f32_16x16x32_bf16 v[24:27], v[186:189], v[230:233], v[24:27]
	v_mfma_f32_16x16x32_bf16 v[16:19], v[178:181], v[238:241], v[16:19]
	v_mfma_f32_16x16x32_bf16 v[8:11], v[186:189], v[238:241], v[8:11]
	v_mfma_f32_16x16x32_bf16 v[4:7], v[178:181], v[246:249], v[4:7]
	v_mfma_f32_16x16x32_bf16 v[0:3], v[186:189], v[246:249], v[0:3]
	s_setprio 0
	s_barrier
	s_add_i32 s72, s72, 2
	s_add_u32 s54, s54, 0x100
	s_addc_u32 s55, s55, 0
	s_add_u32 s45, s45, 0x100
	s_addc_u32 s47, s47, 0
	s_cmp_gt_u32 s72, 13
	s_cbranch_scc0 .LBB0_290
	s_and_b64 vcc, exec, s[22:23]
	s_cbranch_vccz .LBB0_293
	s_barrier

; #define PG8_STAGE(bufoff, gbase, voff) do { _Pragma("unroll") for (int _i = 0; _i < 2; ++_i) \
;         __builtin_amdgcn_global_load_lds((const unsigned*)((const char*)(gbase) + (voff)[_i]), (LAS unsigned*)(lds + (bufoff) + ldsw + _i * 8192), 16, 0, 0); } while (0)
; #define PG8_LDA(dst, b, h) do { _Pragma("unroll") for (int m = 0; m < 4; ++m) _Pragma("unroll") for (int k = 0; k < 2; ++k) dst[m][k] = *(const LAS bf16x8*)(lds + PG8_SA(b, h) + aoff + m * 2048 + k * 1024); } while (0)
; #define PG8_LDB(dst, b, h) do { _Pragma("unroll") for (int n = 0; n < 2; ++n) _Pragma("unroll") for (int k = 0; k < 2; ++k) dst[n][k] = *(const LAS bf16x8*)(lds + PG8_SB(b, h) + boff + n * 2048 + k * 1024); } while (0)
; #define PG8_MMA(ai, bj, At, Bt) do { __builtin_amdgcn_s_setprio(1); _Pragma("unroll") for (int m = 0; m < 4; ++m) _Pragma("unroll") for (int n = 0; n < 2; ++n) _Pragma("unroll") for (int k = 0; k < 2; ++k) \
;         acc[ai][bj][m][n] = __builtin_amdgcn_mfma_f32_16x16x32_bf16(Bt[n][k], At[m][k], acc[ai][bj][m][n], 0, 0, 0); __builtin_amdgcn_s_setprio(0); } while (0)
; #define PG8_WAIT_V(n) asm volatile("s_waitcnt vmcnt(" #n ")" ::: "memory")
; #define PG8_WAIT_L(n) asm volatile("s_waitcnt lgkmcnt(" #n ")" ::: "memory")
; #define PG8_BAR __builtin_amdgcn_s_barrier()
; #define PG8_SCHED __builtin_amdgcn_sched_barrier(0)
; template <class Epi>
; DI void gemm_phase(LAS unsigned char* lds, const Gemm g, const StaticOrder S, const Epi E) {
;     ...
;         for (int t = 0; t < nt; t += 2) {
;             const bool last = (t == nt - 2);
;             const char* a1 = cA + (size_t)(t + 1) * kstep;
;             const char* a2 = last ? nA : cA + (size_t)(t + 2) * kstep; const char* b2 = last ? nB : cB + (size_t)(t + 2) * kstep;
;             const char* a3 = a2 + kstep; const char* b3 = b2 + kstep;
;             PG8_LDB(B0, 0, 0); PG8_LDB(B1, 0, 1); PG8_SCHED; PG8_LDA(At, 0, 0); PG8_STAGE(PG8_SA(1, 1), a1 + hstepA, voffA);
;             PG8_WAIT_V(8); PG8_WAIT_L(0); PG8_BAR; PG8_MMA(0, 0, At, B0); PG8_MMA(0, 1, At, B1); PG8_BAR; PG8_SCHED;
;             PG8_LDA(At, 0, 1); PG8_STAGE(PG8_SB(0, 0), b2, voffB); PG8_STAGE(PG8_SB(0, 1), b2 + hstepB, voffB); PG8_STAGE(PG8_SA(0, 0), a2, voffA);
;             PG8_WAIT_V(8); PG8_WAIT_L(0); PG8_BAR; PG8_MMA(1, 0, At, B0); PG8_MMA(1, 1, At, B1); PG8_BAR; PG8_SCHED;
.LBB0_335:
	s_add_u32 s20, s42, 0xfffc0080
	s_addc_u32 s21, s43, -1
	s_add_i32 s26, 0, 0x10000
	s_cmp_eq_u32 s57, 12
	s_cselect_b32 s65, s59, s21
	s_cselect_b32 s64, s58, s20
	s_cselect_b32 s31, s61, s55
	s_cselect_b32 s30, s60, s3
	s_add_u32 s98, s30, 0x80
	s_addc_u32 s99, s31, 0
	s_add_u32 s100, s64, 0x80
	s_addc_u32 s101, s65, 0
	s_add_i32 s27, 0, 0x14000
	v_add_u32_e32 v140, s26, v220
	v_add_u32_e32 v146, s27, v220
	ds_read_b128 v[128:131], v140
	ds_read_b128 v[132:135], v140 offset:1024
	ds_read_b128 v[136:139], v140 offset:2048
	ds_read_b128 v[140:143], v140 offset:3072
	ds_read_b128 v[168:171], v146
	ds_read_b128 v[172:175], v146 offset:1024
	ds_read_b128 v[176:179], v146 offset:2048
	ds_read_b128 v[180:183], v146 offset:3072
	s_add_i32 m0, s76, 0xc000
	ds_read_b128 v[184:187], v221
	ds_read_b128 v[188:191], v221 offset:1024
	ds_read_b128 v[192:195], v221 offset:2048
	ds_read_b128 v[196:199], v221 offset:3072
	ds_read_b128 v[222:225], v221 offset:4096
	ds_read_b128 v[230:233], v221 offset:5120
	ds_read_b128 v[234:237], v221 offset:6144
	ds_read_b128 v[238:241], v221 offset:7168
	global_load_lds_dwordx4 v164, s[42:43]
	s_add_i32 m0, s76, 0xe000
	s_nop 0
	global_load_lds_dwordx4 v166, s[42:43]
	s_waitcnt vmcnt(8)
	s_waitcnt lgkmcnt(0)
	s_barrier
	s_setprio 1
	s_waitcnt lgkmcnt(0)
	v_mfma_f32_16x16x32_bf16 v[124:127], v[128:131], v[184:187], v[124:127]
	v_mfma_f32_16x16x32_bf16 v[120:123], v[136:139], v[184:187], v[120:123]
	v_mfma_f32_16x16x32_bf16 v[108:111], v[128:131], v[192:195], v[108:111]
	v_mfma_f32_16x16x32_bf16 v[104:107], v[136:139], v[192:195], v[104:107]
	v_mfma_f32_16x16x32_bf16 v[92:95], v[128:131], v[222:225], v[92:95]
	v_mfma_f32_16x16x32_bf16 v[88:91], v[136:139], v[222:225], v[88:91]
	v_mfma_f32_16x16x32_bf16 v[76:79], v[128:131], v[234:237], v[76:79]
	v_mfma_f32_16x16x32_bf16 v[72:75], v[136:139], v[234:237], v[72:75]
	v_mfma_f32_16x16x32_bf16 v[124:127], v[132:135], v[188:191], v[124:127]
	v_mfma_f32_16x16x32_bf16 v[120:123], v[140:143], v[188:191], v[120:123]
	v_mfma_f32_16x16x32_bf16 v[108:111], v[132:135], v[196:199], v[108:111]
	v_mfma_f32_16x16x32_bf16 v[104:107], v[140:143], v[196:199], v[104:107]
	v_mfma_f32_16x16x32_bf16 v[92:95], v[132:135], v[230:233], v[92:95]
	v_mfma_f32_16x16x32_bf16 v[88:91], v[140:143], v[230:233], v[88:91]
	v_mfma_f32_16x16x32_bf16 v[76:79], v[132:135], v[238:241], v[76:79]
	v_mfma_f32_16x16x32_bf16 v[72:75], v[140:143], v[238:241], v[72:75]
	v_mfma_f32_16x16x32_bf16 v[116:119], v[168:171], v[184:187], v[116:119]
	v_mfma_f32_16x16x32_bf16 v[112:115], v[176:179], v[184:187], v[112:115]
	v_mfma_f32_16x16x32_bf16 v[100:103], v[168:171], v[192:195], v[100:103]
	v_mfma_f32_16x16x32_bf16 v[96:99], v[176:179], v[192:195], v[96:99]
	v_mfma_f32_16x16x32_bf16 v[84:87], v[168:171], v[222:225], v[84:87]
	v_mfma_f32_16x16x32_bf16 v[80:83], v[176:179], v[222:225], v[80:83]
	v_mfma_f32_16x16x32_bf16 v[68:71], v[168:171], v[234:237], v[68:71]
	v_mfma_f32_16x16x32_bf16 v[64:67], v[176:179], v[234:237], v[64:67]
	v_mfma_f32_16x16x32_bf16 v[116:119], v[172:175], v[188:191], v[116:119]
	v_mfma_f32_16x16x32_bf16 v[112:115], v[180:183], v[188:191], v[112:115]
	v_mfma_f32_16x16x32_bf16 v[100:103], v[172:175], v[196:199], v[100:103]
	v_mfma_f32_16x16x32_bf16 v[96:99], v[180:183], v[196:199], v[96:99]
	v_mfma_f32_16x16x32_bf16 v[84:87], v[172:175], v[230:233], v[84:87]
	v_mfma_f32_16x16x32_bf16 v[80:83], v[180:183], v[230:233], v[80:83]
	v_mfma_f32_16x16x32_bf16 v[68:71], v[172:175], v[238:241], v[68:71]
	v_mfma_f32_16x16x32_bf16 v[64:67], v[180:183], v[238:241], v[64:67]
	s_setprio 0
	s_barrier
	s_add_i32 s20, s26, s66
	s_mov_b32 m0, s20
	ds_read_b128 v[184:187], v221 offset:16384
	ds_read_b128 v[188:191], v221 offset:17408
	ds_read_b128 v[192:195], v221 offset:18432
	ds_read_b128 v[196:199], v221 offset:19456
	ds_read_b128 v[222:225], v221 offset:20480
	ds_read_b128 v[230:233], v221 offset:21504
	ds_read_b128 v[234:237], v221 offset:22528
	ds_read_b128 v[238:241], v221 offset:23552
	global_load_lds_dwordx4 v158, s[30:31]
	s_add_i32 m0, s20, 0x2000
	s_add_u32 s20, s30, 0x40000
	s_addc_u32 s21, s31, 0
	s_add_i32 s26, s27, s66
	global_load_lds_dwordx4 v162, s[30:31]
	s_mov_b32 m0, s26
	s_nop 0
	global_load_lds_dwordx4 v158, s[20:21]
	s_add_i32 m0, s26, 0x2000
	s_nop 0
	global_load_lds_dwordx4 v162, s[20:21]
	s_mov_b32 m0, s76
	s_nop 0
	global_load_lds_dwordx4 v144, s[64:65]
	s_mov_b32 m0, s77
	s_nop 0
	global_load_lds_dwordx4 v160, s[64:65]
	s_waitcnt vmcnt(8)
	s_waitcnt lgkmcnt(0)
	s_barrier
	s_setprio 1
	s_waitcnt lgkmcnt(0)
	v_mfma_f32_16x16x32_bf16 v[60:63], v[128:131], v[184:187], v[60:63]
	v_mfma_f32_16x16x32_bf16 v[56:59], v[136:139], v[184:187], v[56:59]
	v_mfma_f32_16x16x32_bf16 v[44:47], v[128:131], v[192:195], v[44:47]
	v_mfma_f32_16x16x32_bf16 v[40:43], v[136:139], v[192:195], v[40:43]
	v_mfma_f32_16x16x32_bf16 v[28:31], v[128:131], v[222:225], v[28:31]
	v_mfma_f32_16x16x32_bf16 v[24:27], v[136:139], v[222:225], v[24:27]
	v_mfma_f32_16x16x32_bf16 v[12:15], v[128:131], v[234:237], v[12:15]
	v_mfma_f32_16x16x32_bf16 v[8:11], v[136:139], v[234:237], v[8:11]
	v_mfma_f32_16x16x32_bf16 v[60:63], v[132:135], v[188:191], v[60:63]
	v_mfma_f32_16x16x32_bf16 v[56:59], v[140:143], v[188:191], v[56:59]
	v_mfma_f32_16x16x32_bf16 v[44:47], v[132:135], v[196:199], v[44:47]
	v_mfma_f32_16x16x32_bf16 v[40:43], v[140:143], v[196:199], v[40:43]
	v_mfma_f32_16x16x32_bf16 v[28:31], v[132:135], v[230:233], v[28:31]
	v_mfma_f32_16x16x32_bf16 v[24:27], v[140:143], v[230:233], v[24:27]
	v_mfma_f32_16x16x32_bf16 v[12:15], v[132:135], v[238:241], v[12:15]
	v_mfma_f32_16x16x32_bf16 v[8:11], v[140:143], v[238:241], v[8:11]
	v_mfma_f32_16x16x32_bf16 v[52:55], v[168:171], v[184:187], v[52:55]
	v_mfma_f32_16x16x32_bf16 v[48:51], v[176:179], v[184:187], v[48:51]
	v_mfma_f32_16x16x32_bf16 v[36:39], v[168:171], v[192:195], v[36:39]
	v_mfma_f32_16x16x32_bf16 v[32:35], v[176:179], v[192:195], v[32:35]
	v_mfma_f32_16x16x32_bf16 v[20:23], v[168:171], v[222:225], v[20:23]
	v_mfma_f32_16x16x32_bf16 v[16:19], v[176:179], v[222:225], v[16:19]
	v_mfma_f32_16x16x32_bf16 v[4:7], v[168:171], v[234:237], v[4:7]
	v_mfma_f32_16x16x32_bf16 v[0:3], v[176:179], v[234:237], v[0:3]
	v_mfma_f32_16x16x32_bf16 v[52:55], v[172:175], v[188:191], v[52:55]
	v_mfma_f32_16x16x32_bf16 v[48:51], v[180:183], v[188:191], v[48:51]
	v_mfma_f32_16x16x32_bf16 v[36:39], v[172:175], v[196:199], v[36:39]
	v_mfma_f32_16x16x32_bf16 v[32:35], v[180:183], v[196:199], v[32:35]
	v_mfma_f32_16x16x32_bf16 v[20:23], v[172:175], v[230:233], v[20:23]
	v_mfma_f32_16x16x32_bf16 v[16:19], v[180:183], v[230:233], v[16:19]
	v_mfma_f32_16x16x32_bf16 v[4:7], v[172:175], v[238:241], v[4:7]
	v_mfma_f32_16x16x32_bf16 v[0:3], v[180:183], v[238:241], v[0:3]
	s_setprio 0
	s_barrier
; #define PG8_STAGE(bufoff, gbase, voff) do { _Pragma("unroll") for (int _i = 0; _i < 2; ++_i) \
;         __builtin_amdgcn_global_load_lds((const unsigned*)((const char*)(gbase) + (voff)[_i]), (LAS unsigned*)(lds + (bufoff) + ldsw + _i * 8192), 16, 0, 0); } while (0)
; #define PG8_LDA(dst, b, h) do { _Pragma("unroll") for (int m = 0; m < 4; ++m) _Pragma("unroll") for (int k = 0; k < 2; ++k) dst[m][k] = *(const LAS bf16x8*)(lds + PG8_SA(b, h) + aoff + m * 2048 + k * 1024); } while (0)
; #define PG8_LDB(dst, b, h) do { _Pragma("unroll") for (int n = 0; n < 2; ++n) _Pragma("unroll") for (int k = 0; k < 2; ++k) dst[n][k] = *(const LAS bf16x8*)(lds + PG8_SB(b, h) + boff + n * 2048 + k * 1024); } while (0)
; #define PG8_MMA(ai, bj, At, Bt) do { __builtin_amdgcn_s_setprio(1); _Pragma("unroll") for (int m = 0; m < 4; ++m) _Pragma("unroll") for (int n = 0; n < 2; ++n) _Pragma("unroll") for (int k = 0; k < 2; ++k) \
;         acc[ai][bj][m][n] = __builtin_amdgcn_mfma_f32_16x16x32_bf16(Bt[n][k], At[m][k], acc[ai][bj][m][n], 0, 0, 0); __builtin_amdgcn_s_setprio(0); } while (0)
; #define PG8_WAIT_V(n) asm volatile("s_waitcnt vmcnt(" #n ")" ::: "memory")
; #define PG8_WAIT_L(n) asm volatile("s_waitcnt lgkmcnt(" #n ")" ::: "memory")
; #define PG8_BAR __builtin_amdgcn_s_barrier()
; #define PG8_SCHED __builtin_amdgcn_sched_barrier(0)
; template <class Epi>
; DI void gemm_phase(LAS unsigned char* lds, const Gemm g, const StaticOrder S, const Epi E) {
;     ...
;             PG8_LDB(B0, 1, 0); PG8_LDB(B1, 1, 1); PG8_SCHED; PG8_LDA(At, 1, 0); PG8_STAGE(PG8_SA(0, 1), a2 + hstepA, voffA);
;             PG8_WAIT_V(8); PG8_WAIT_L(0); PG8_BAR; PG8_MMA(0, 0, At, B0); PG8_MMA(0, 1, At, B1); PG8_BAR; PG8_SCHED;
;             PG8_LDA(At, 1, 1); PG8_STAGE(PG8_SB(1, 0), b3, voffB); PG8_STAGE(PG8_SB(1, 1), b3 + hstepB, voffB); PG8_STAGE(PG8_SA(1, 0), a3, voffA);
;             PG8_WAIT_V(8); PG8_WAIT_L(0); PG8_BAR; PG8_MMA(1, 0, At, B0); PG8_MMA(1, 1, At, B1); PG8_BAR; PG8_SCHED;
;         }
;         if (wr == 0) PG8_BAR;
	s_add_i32 s26, 0, 0x1c000
	v_add_u32_e32 v140, s74, v220
	v_add_u32_e32 v146, s26, v220
	ds_read_b128 v[128:131], v140
	ds_read_b128 v[132:135], v140 offset:1024
	ds_read_b128 v[136:139], v140 offset:2048
	ds_read_b128 v[140:143], v140 offset:3072
	ds_read_b128 v[168:171], v146
	ds_read_b128 v[172:175], v146 offset:1024
	ds_read_b128 v[176:179], v146 offset:2048
	ds_read_b128 v[180:183], v146 offset:3072
	s_add_u32 s20, s64, 0x40000
	s_addc_u32 s21, s65, 0
	s_mov_b32 m0, s78
	ds_read_b128 v[184:187], v221 offset:32768
	ds_read_b128 v[188:191], v221 offset:33792
	ds_read_b128 v[192:195], v221 offset:34816
	ds_read_b128 v[196:199], v221 offset:35840
	ds_read_b128 v[222:225], v221 offset:36864
	ds_read_b128 v[230:233], v221 offset:37888
	ds_read_b128 v[234:237], v221 offset:38912
	ds_read_b128 v[238:241], v221 offset:39936
	global_load_lds_dwordx4 v144, s[20:21]
	s_mov_b32 m0, s79
	s_nop 0
	global_load_lds_dwordx4 v160, s[20:21]
	s_waitcnt vmcnt(8)
	s_waitcnt lgkmcnt(0)
	s_barrier
	s_setprio 1
	s_waitcnt lgkmcnt(0)
	v_mfma_f32_16x16x32_bf16 v[124:127], v[128:131], v[184:187], v[124:127]
	v_mfma_f32_16x16x32_bf16 v[120:123], v[136:139], v[184:187], v[120:123]
	v_mfma_f32_16x16x32_bf16 v[108:111], v[128:131], v[192:195], v[108:111]
	v_mfma_f32_16x16x32_bf16 v[104:107], v[136:139], v[192:195], v[104:107]
	v_mfma_f32_16x16x32_bf16 v[92:95], v[128:131], v[222:225], v[92:95]
	v_mfma_f32_16x16x32_bf16 v[88:91], v[136:139], v[222:225], v[88:91]
	v_mfma_f32_16x16x32_bf16 v[76:79], v[128:131], v[234:237], v[76:79]
	v_mfma_f32_16x16x32_bf16 v[72:75], v[136:139], v[234:237], v[72:75]
	v_mfma_f32_16x16x32_bf16 v[124:127], v[132:135], v[188:191], v[124:127]
	v_mfma_f32_16x16x32_bf16 v[120:123], v[140:143], v[188:191], v[120:123]
	v_mfma_f32_16x16x32_bf16 v[108:111], v[132:135], v[196:199], v[108:111]
	v_mfma_f32_16x16x32_bf16 v[104:107], v[140:143], v[196:199], v[104:107]
	v_mfma_f32_16x16x32_bf16 v[92:95], v[132:135], v[230:233], v[92:95]
	v_mfma_f32_16x16x32_bf16 v[88:91], v[140:143], v[230:233], v[88:91]
	v_mfma_f32_16x16x32_bf16 v[76:79], v[132:135], v[238:241], v[76:79]
	v_mfma_f32_16x16x32_bf16 v[72:75], v[140:143], v[238:241], v[72:75]
	v_mfma_f32_16x16x32_bf16 v[116:119], v[168:171], v[184:187], v[116:119]
	v_mfma_f32_16x16x32_bf16 v[112:115], v[176:179], v[184:187], v[112:115]
	v_mfma_f32_16x16x32_bf16 v[100:103], v[168:171], v[192:195], v[100:103]
	v_mfma_f32_16x16x32_bf16 v[96:99], v[176:179], v[192:195], v[96:99]
	v_mfma_f32_16x16x32_bf16 v[84:87], v[168:171], v[222:225], v[84:87]
	v_mfma_f32_16x16x32_bf16 v[80:83], v[176:179], v[222:225], v[80:83]
	v_mfma_f32_16x16x32_bf16 v[68:71], v[168:171], v[234:237], v[68:71]
	v_mfma_f32_16x16x32_bf16 v[64:67], v[176:179], v[234:237], v[64:67]
	v_mfma_f32_16x16x32_bf16 v[116:119], v[172:175], v[188:191], v[116:119]
	v_mfma_f32_16x16x32_bf16 v[112:115], v[180:183], v[188:191], v[112:115]
	v_mfma_f32_16x16x32_bf16 v[100:103], v[172:175], v[196:199], v[100:103]
	v_mfma_f32_16x16x32_bf16 v[96:99], v[180:183], v[196:199], v[96:99]
	v_mfma_f32_16x16x32_bf16 v[84:87], v[172:175], v[230:233], v[84:87]
	v_mfma_f32_16x16x32_bf16 v[80:83], v[180:183], v[230:233], v[80:83]
	v_mfma_f32_16x16x32_bf16 v[68:71], v[172:175], v[238:241], v[68:71]
	v_mfma_f32_16x16x32_bf16 v[64:67], v[180:183], v[238:241], v[64:67]
	s_setprio 0
	s_barrier
	s_add_i32 s20, s74, s66
	s_mov_b32 m0, s20
	ds_read_b128 v[184:187], v221 offset:49152
	ds_read_b128 v[188:191], v221 offset:50176
	ds_read_b128 v[192:195], v221 offset:51200
	ds_read_b128 v[196:199], v221 offset:52224
	ds_read_b128 v[222:225], v221 offset:53248
	ds_read_b128 v[230:233], v221 offset:54272
	ds_read_b128 v[234:237], v221 offset:55296
	ds_read_b128 v[238:241], v221 offset:56320
	global_load_lds_dwordx4 v158, s[98:99]
	s_add_i32 m0, s20, 0x2000
	s_add_u32 s20, s30, 0x40080
	s_addc_u32 s21, s31, 0
	s_add_i32 s26, s26, s66
	global_load_lds_dwordx4 v162, s[98:99]
	s_mov_b32 m0, s26
	s_nop 0
	global_load_lds_dwordx4 v158, s[20:21]
	s_add_i32 m0, s26, 0x2000
	s_nop 0
	global_load_lds_dwordx4 v162, s[20:21]
	s_mov_b32 m0, s88
	s_nop 0
	global_load_lds_dwordx4 v144, s[100:101]
	s_mov_b32 m0, s22
	s_nop 0
	global_load_lds_dwordx4 v160, s[100:101]
	s_waitcnt vmcnt(8)
	s_waitcnt lgkmcnt(0)
	s_barrier
	s_setprio 1
	s_waitcnt lgkmcnt(0)
	v_mfma_f32_16x16x32_bf16 v[60:63], v[128:131], v[184:187], v[60:63]
	v_mfma_f32_16x16x32_bf16 v[56:59], v[136:139], v[184:187], v[56:59]
	v_mfma_f32_16x16x32_bf16 v[44:47], v[128:131], v[192:195], v[44:47]
	v_mfma_f32_16x16x32_bf16 v[40:43], v[136:139], v[192:195], v[40:43]
	v_mfma_f32_16x16x32_bf16 v[28:31], v[128:131], v[222:225], v[28:31]
	v_mfma_f32_16x16x32_bf16 v[24:27], v[136:139], v[222:225], v[24:27]
	v_mfma_f32_16x16x32_bf16 v[12:15], v[128:131], v[234:237], v[12:15]
	v_mfma_f32_16x16x32_bf16 v[8:11], v[136:139], v[234:237], v[8:11]
	v_mfma_f32_16x16x32_bf16 v[60:63], v[132:135], v[188:191], v[60:63]
	v_mfma_f32_16x16x32_bf16 v[56:59], v[140:143], v[188:191], v[56:59]
	v_mfma_f32_16x16x32_bf16 v[44:47], v[132:135], v[196:199], v[44:47]
	v_mfma_f32_16x16x32_bf16 v[40:43], v[140:143], v[196:199], v[40:43]
	v_mfma_f32_16x16x32_bf16 v[28:31], v[132:135], v[230:233], v[28:31]
	v_mfma_f32_16x16x32_bf16 v[24:27], v[140:143], v[230:233], v[24:27]
	v_mfma_f32_16x16x32_bf16 v[12:15], v[132:135], v[238:241], v[12:15]
	v_mfma_f32_16x16x32_bf16 v[8:11], v[140:143], v[238:241], v[8:11]
	v_mfma_f32_16x16x32_bf16 v[52:55], v[168:171], v[184:187], v[52:55]
	v_mfma_f32_16x16x32_bf16 v[48:51], v[176:179], v[184:187], v[48:51]
	v_mfma_f32_16x16x32_bf16 v[36:39], v[168:171], v[192:195], v[36:39]
	v_mfma_f32_16x16x32_bf16 v[32:35], v[176:179], v[192:195], v[32:35]
	v_mfma_f32_16x16x32_bf16 v[20:23], v[168:171], v[222:225], v[20:23]
	v_mfma_f32_16x16x32_bf16 v[16:19], v[176:179], v[222:225], v[16:19]
	v_mfma_f32_16x16x32_bf16 v[4:7], v[168:171], v[234:237], v[4:7]
	v_mfma_f32_16x16x32_bf16 v[0:3], v[176:179], v[234:237], v[0:3]
	v_mfma_f32_16x16x32_bf16 v[52:55], v[172:175], v[188:191], v[52:55]
	v_mfma_f32_16x16x32_bf16 v[48:51], v[180:183], v[188:191], v[48:51]
	v_mfma_f32_16x16x32_bf16 v[36:39], v[172:175], v[196:199], v[36:39]
	v_mfma_f32_16x16x32_bf16 v[32:35], v[180:183], v[196:199], v[32:35]
	v_mfma_f32_16x16x32_bf16 v[20:23], v[172:175], v[230:233], v[20:23]
	v_mfma_f32_16x16x32_bf16 v[16:19], v[180:183], v[230:233], v[16:19]
	v_mfma_f32_16x16x32_bf16 v[4:7], v[172:175], v[238:241], v[4:7]
	v_mfma_f32_16x16x32_bf16 v[0:3], v[180:183], v[238:241], v[0:3]
	s_setprio 0
	s_barrier
	s_add_i32 s57, s57, 2
	s_add_u32 s42, s42, 0x100
	s_addc_u32 s43, s43, 0
	s_add_u32 s3, s3, 0x100
	s_addc_u32 s55, s55, 0
	s_cmp_gt_u32 s57, 13
	s_cbranch_scc0 .LBB0_335
	s_and_b64 vcc, exec, s[52:53]
	s_cbranch_vccz .LBB0_338
	s_barrier

; #define PG8_STAGE(bufoff, gbase, voff) do { _Pragma("unroll") for (int _i = 0; _i < 2; ++_i) \
;         __builtin_amdgcn_global_load_lds((const unsigned*)((const char*)(gbase) + (voff)[_i]), (LAS unsigned*)(lds + (bufoff) + ldsw + _i * 8192), 16, 0, 0); } while (0)
; #define PG8_LDA(dst, b, h) do { _Pragma("unroll") for (int m = 0; m < 4; ++m) _Pragma("unroll") for (int k = 0; k < 2; ++k) dst[m][k] = *(const LAS bf16x8*)(lds + PG8_SA(b, h) + aoff + m * 2048 + k * 1024); } while (0)
; #define PG8_LDB(dst, b, h) do { _Pragma("unroll") for (int n = 0; n < 2; ++n) _Pragma("unroll") for (int k = 0; k < 2; ++k) dst[n][k] = *(const LAS bf16x8*)(lds + PG8_SB(b, h) + boff + n * 2048 + k * 1024); } while (0)
; #define PG8_MMA(ai, bj, At, Bt) do { __builtin_amdgcn_s_setprio(1); _Pragma("unroll") for (int m = 0; m < 4; ++m) _Pragma("unroll") for (int n = 0; n < 2; ++n) _Pragma("unroll") for (int k = 0; k < 2; ++k) \
;         acc[ai][bj][m][n] = __builtin_amdgcn_mfma_f32_16x16x32_bf16(Bt[n][k], At[m][k], acc[ai][bj][m][n], 0, 0, 0); __builtin_amdgcn_s_setprio(0); } while (0)
; #define PG8_WAIT_V(n) asm volatile("s_waitcnt vmcnt(" #n ")" ::: "memory")
; #define PG8_WAIT_L(n) asm volatile("s_waitcnt lgkmcnt(" #n ")" ::: "memory")
; #define PG8_BAR __builtin_amdgcn_s_barrier()
; #define PG8_SCHED __builtin_amdgcn_sched_barrier(0)
; template <class Epi>
; DI void gemm_phase(LAS unsigned char* lds, const Gemm g, const StaticOrder S, const Epi E) {
;     ...
;         for (int t = 0; t < nt; t += 2) {
;             const bool last = (t == nt - 2);
;             const char* a1 = cA + (size_t)(t + 1) * kstep;
;             const char* a2 = last ? nA : cA + (size_t)(t + 2) * kstep; const char* b2 = last ? nB : cB + (size_t)(t + 2) * kstep;
;             const char* a3 = a2 + kstep; const char* b3 = b2 + kstep;
;             PG8_LDB(B0, 0, 0); PG8_LDB(B1, 0, 1); PG8_SCHED; PG8_LDA(At, 0, 0); PG8_STAGE(PG8_SA(1, 1), a1 + hstepA, voffA);
;             PG8_WAIT_V(8); PG8_WAIT_L(0); PG8_BAR; PG8_MMA(0, 0, At, B0); PG8_MMA(0, 1, At, B1); PG8_BAR; PG8_SCHED;
;             PG8_LDA(At, 0, 1); PG8_STAGE(PG8_SB(0, 0), b2, voffB); PG8_STAGE(PG8_SB(0, 1), b2 + hstepB, voffB); PG8_STAGE(PG8_SA(0, 0), a2, voffA);
;             PG8_WAIT_V(8); PG8_WAIT_L(0); PG8_BAR; PG8_MMA(1, 0, At, B0); PG8_MMA(1, 1, At, B1); PG8_BAR; PG8_SCHED;
.LBB0_430:
	s_add_i32 vcc_lo, s30, 2
	s_add_u32 s20, s42, 0x80
	s_addc_u32 s21, s43, 0
	s_add_i32 vcc_hi, 0, 0x10000
	s_cmp_eq_u32 s65, s30
	s_cselect_b32 s31, s67, s21
	s_cselect_b32 s30, s66, s20
	s_cselect_b32 s21, s69, s45
	s_cselect_b32 s20, s68, s44
	s_add_u32 s98, s20, 0x80
	s_addc_u32 s99, s21, 0
	s_add_u32 s100, s98, s77
	s_addc_u32 s101, s99, 0
	s_add_i32 s26, 0, 0x14000
	v_add_u32_e32 v162, vcc_hi, v175
	v_add_u32_e32 v177, s26, v175
	ds_read_b128 v[128:131], v162
	ds_read_b128 v[142:145], v162 offset:1024
	ds_read_b128 v[158:161], v162 offset:2048
	ds_read_b128 v[162:165], v162 offset:3072
	ds_read_b128 v[166:169], v177
	ds_read_b128 v[170:173], v177 offset:1024
	ds_read_b128 v[178:181], v177 offset:2048
	ds_read_b128 v[182:185], v177 offset:3072
	s_add_i32 m0, s51, 0xc000
	ds_read_b128 v[186:189], v176
	ds_read_b128 v[190:193], v176 offset:1024
	ds_read_b128 v[194:197], v176 offset:2048
	ds_read_b128 v[220:223], v176 offset:3072
	ds_read_b128 v[230:233], v176 offset:4096
	ds_read_b128 v[234:237], v176 offset:5120
	ds_read_b128 v[238:241], v176 offset:6144
	ds_read_b128 v[242:245], v176 offset:7168
	global_load_lds_dwordx4 v138, s[42:43]
	s_add_i32 m0, s51, 0xe000
	s_nop 0
	global_load_lds_dwordx4 v140, s[42:43]
	s_waitcnt vmcnt(8)
	s_waitcnt lgkmcnt(0)
	s_barrier
	s_setprio 1
	s_waitcnt lgkmcnt(0)
	v_mfma_f32_16x16x32_bf16 v[124:127], v[128:131], v[186:189], v[124:127]
	v_mfma_f32_16x16x32_bf16 v[120:123], v[158:161], v[186:189], v[120:123]
	v_mfma_f32_16x16x32_bf16 v[116:119], v[128:131], v[194:197], v[116:119]
	v_mfma_f32_16x16x32_bf16 v[112:115], v[158:161], v[194:197], v[112:115]
	v_mfma_f32_16x16x32_bf16 v[108:111], v[128:131], v[230:233], v[108:111]
	v_mfma_f32_16x16x32_bf16 v[104:107], v[158:161], v[230:233], v[104:107]
	v_mfma_f32_16x16x32_bf16 v[100:103], v[128:131], v[238:241], v[100:103]
	v_mfma_f32_16x16x32_bf16 v[96:99], v[158:161], v[238:241], v[96:99]
	v_mfma_f32_16x16x32_bf16 v[124:127], v[142:145], v[190:193], v[124:127]
	v_mfma_f32_16x16x32_bf16 v[120:123], v[162:165], v[190:193], v[120:123]
	v_mfma_f32_16x16x32_bf16 v[116:119], v[142:145], v[220:223], v[116:119]
	v_mfma_f32_16x16x32_bf16 v[112:115], v[162:165], v[220:223], v[112:115]
	v_mfma_f32_16x16x32_bf16 v[108:111], v[142:145], v[234:237], v[108:111]
	v_mfma_f32_16x16x32_bf16 v[104:107], v[162:165], v[234:237], v[104:107]
	v_mfma_f32_16x16x32_bf16 v[100:103], v[142:145], v[242:245], v[100:103]
	v_mfma_f32_16x16x32_bf16 v[96:99], v[162:165], v[242:245], v[96:99]
	v_mfma_f32_16x16x32_bf16 v[60:63], v[166:169], v[186:189], v[60:63]
	v_mfma_f32_16x16x32_bf16 v[56:59], v[178:181], v[186:189], v[56:59]
	v_mfma_f32_16x16x32_bf16 v[52:55], v[166:169], v[194:197], v[52:55]
	v_mfma_f32_16x16x32_bf16 v[48:51], v[178:181], v[194:197], v[48:51]
	v_mfma_f32_16x16x32_bf16 v[44:47], v[166:169], v[230:233], v[44:47]
	v_mfma_f32_16x16x32_bf16 v[40:43], v[178:181], v[230:233], v[40:43]
	v_mfma_f32_16x16x32_bf16 v[36:39], v[166:169], v[238:241], v[36:39]
	v_mfma_f32_16x16x32_bf16 v[32:35], v[178:181], v[238:241], v[32:35]
	v_mfma_f32_16x16x32_bf16 v[60:63], v[170:173], v[190:193], v[60:63]
	v_mfma_f32_16x16x32_bf16 v[56:59], v[182:185], v[190:193], v[56:59]
	v_mfma_f32_16x16x32_bf16 v[52:55], v[170:173], v[220:223], v[52:55]
	v_mfma_f32_16x16x32_bf16 v[48:51], v[182:185], v[220:223], v[48:51]
	v_mfma_f32_16x16x32_bf16 v[44:47], v[170:173], v[234:237], v[44:47]
	v_mfma_f32_16x16x32_bf16 v[40:43], v[182:185], v[234:237], v[40:43]
	v_mfma_f32_16x16x32_bf16 v[36:39], v[170:173], v[242:245], v[36:39]
	v_mfma_f32_16x16x32_bf16 v[32:35], v[182:185], v[242:245], v[32:35]
	s_setprio 0
	s_barrier
	s_add_i32 s27, vcc_hi, s81
	s_mov_b32 m0, s27
	ds_read_b128 v[186:189], v176 offset:16384
	ds_read_b128 v[190:193], v176 offset:17408
	ds_read_b128 v[194:197], v176 offset:18432
	ds_read_b128 v[220:223], v176 offset:19456
	ds_read_b128 v[230:233], v176 offset:20480
	ds_read_b128 v[234:237], v176 offset:21504
	ds_read_b128 v[238:241], v176 offset:22528
	ds_read_b128 v[242:245], v176 offset:23552
	global_load_lds_dwordx4 v146, s[20:21]
	s_add_i32 m0, s27, 0x2000
	s_add_i32 s26, s26, s81
	global_load_lds_dwordx4 v136, s[20:21]
	s_add_u32 s20, s20, s77
	s_addc_u32 s21, s21, 0
	s_mov_b32 m0, s26
	s_nop 0
	global_load_lds_dwordx4 v146, s[20:21]
	s_add_i32 m0, s26, 0x2000
	s_nop 0
	global_load_lds_dwordx4 v136, s[20:21]
	s_mov_b32 m0, s51
	s_nop 0
	global_load_lds_dwordx4 v132, s[30:31]
	s_mov_b32 m0, s70
	s_nop 0
	global_load_lds_dwordx4 v134, s[30:31]
	s_waitcnt vmcnt(8)
	s_waitcnt lgkmcnt(0)
	s_barrier
; #define PG8_STAGE(bufoff, gbase, voff) do { _Pragma("unroll") for (int _i = 0; _i < 2; ++_i) \
;         __builtin_amdgcn_global_load_lds((const unsigned*)((const char*)(gbase) + (voff)[_i]), (LAS unsigned*)(lds + (bufoff) + ldsw + _i * 8192), 16, 0, 0); } while (0)
; #define PG8_LDA(dst, b, h) do { _Pragma("unroll") for (int m = 0; m < 4; ++m) _Pragma("unroll") for (int k = 0; k < 2; ++k) dst[m][k] = *(const LAS bf16x8*)(lds + PG8_SA(b, h) + aoff + m * 2048 + k * 1024); } while (0)
; #define PG8_LDB(dst, b, h) do { _Pragma("unroll") for (int n = 0; n < 2; ++n) _Pragma("unroll") for (int k = 0; k < 2; ++k) dst[n][k] = *(const LAS bf16x8*)(lds + PG8_SB(b, h) + boff + n * 2048 + k * 1024); } while (0)
; #define PG8_MMA(ai, bj, At, Bt) do { __builtin_amdgcn_s_setprio(1); _Pragma("unroll") for (int m = 0; m < 4; ++m) _Pragma("unroll") for (int n = 0; n < 2; ++n) _Pragma("unroll") for (int k = 0; k < 2; ++k) \
;         acc[ai][bj][m][n] = __builtin_amdgcn_mfma_f32_16x16x32_bf16(Bt[n][k], At[m][k], acc[ai][bj][m][n], 0, 0, 0); __builtin_amdgcn_s_setprio(0); } while (0)
; #define PG8_WAIT_V(n) asm volatile("s_waitcnt vmcnt(" #n ")" ::: "memory")
; #define PG8_WAIT_L(n) asm volatile("s_waitcnt lgkmcnt(" #n ")" ::: "memory")
; #define PG8_BAR __builtin_amdgcn_s_barrier()
; #define PG8_SCHED __builtin_amdgcn_sched_barrier(0)
; template <class Epi>
; DI void gemm_phase(LAS unsigned char* lds, const Gemm g, const StaticOrder S, const Epi E) {
;     ...
;             PG8_WAIT_V(8); PG8_WAIT_L(0); PG8_BAR; PG8_MMA(0, 0, At, B0); PG8_MMA(0, 1, At, B1); PG8_BAR; PG8_SCHED;
;             PG8_LDA(At, 0, 1); PG8_STAGE(PG8_SB(0, 0), b2, voffB); PG8_STAGE(PG8_SB(0, 1), b2 + hstepB, voffB); PG8_STAGE(PG8_SA(0, 0), a2, voffA);
;             PG8_WAIT_V(8); PG8_WAIT_L(0); PG8_BAR; PG8_MMA(1, 0, At, B0); PG8_MMA(1, 1, At, B1); PG8_BAR; PG8_SCHED;
;             PG8_LDB(B0, 1, 0); PG8_LDB(B1, 1, 1); PG8_SCHED; PG8_LDA(At, 1, 0); PG8_STAGE(PG8_SA(0, 1), a2 + hstepA, voffA);
;             PG8_WAIT_V(8); PG8_WAIT_L(0); PG8_BAR; PG8_MMA(0, 0, At, B0); PG8_MMA(0, 1, At, B1); PG8_BAR; PG8_SCHED;
	s_setprio 1
	s_waitcnt lgkmcnt(0)
	v_mfma_f32_16x16x32_bf16 v[92:95], v[128:131], v[186:189], v[92:95]
	v_mfma_f32_16x16x32_bf16 v[88:91], v[158:161], v[186:189], v[88:91]
	v_mfma_f32_16x16x32_bf16 v[84:87], v[128:131], v[194:197], v[84:87]
	v_mfma_f32_16x16x32_bf16 v[80:83], v[158:161], v[194:197], v[80:83]
	v_mfma_f32_16x16x32_bf16 v[76:79], v[128:131], v[230:233], v[76:79]
	v_mfma_f32_16x16x32_bf16 v[72:75], v[158:161], v[230:233], v[72:75]
	v_mfma_f32_16x16x32_bf16 v[68:71], v[128:131], v[238:241], v[68:71]
	v_mfma_f32_16x16x32_bf16 v[64:67], v[158:161], v[238:241], v[64:67]
	v_mfma_f32_16x16x32_bf16 v[92:95], v[142:145], v[190:193], v[92:95]
	v_mfma_f32_16x16x32_bf16 v[88:91], v[162:165], v[190:193], v[88:91]
	v_mfma_f32_16x16x32_bf16 v[84:87], v[142:145], v[220:223], v[84:87]
	v_mfma_f32_16x16x32_bf16 v[80:83], v[162:165], v[220:223], v[80:83]
	v_mfma_f32_16x16x32_bf16 v[76:79], v[142:145], v[234:237], v[76:79]
	v_mfma_f32_16x16x32_bf16 v[72:75], v[162:165], v[234:237], v[72:75]
	v_mfma_f32_16x16x32_bf16 v[68:71], v[142:145], v[242:245], v[68:71]
	v_mfma_f32_16x16x32_bf16 v[64:67], v[162:165], v[242:245], v[64:67]
	v_mfma_f32_16x16x32_bf16 v[28:31], v[166:169], v[186:189], v[28:31]
	v_mfma_f32_16x16x32_bf16 v[24:27], v[178:181], v[186:189], v[24:27]
	v_mfma_f32_16x16x32_bf16 v[20:23], v[166:169], v[194:197], v[20:23]
	v_mfma_f32_16x16x32_bf16 v[16:19], v[178:181], v[194:197], v[16:19]
	v_mfma_f32_16x16x32_bf16 v[12:15], v[166:169], v[230:233], v[12:15]
	v_mfma_f32_16x16x32_bf16 v[8:11], v[178:181], v[230:233], v[8:11]
	v_mfma_f32_16x16x32_bf16 v[4:7], v[166:169], v[238:241], v[4:7]
	v_mfma_f32_16x16x32_bf16 v[0:3], v[178:181], v[238:241], v[0:3]
	v_mfma_f32_16x16x32_bf16 v[28:31], v[170:173], v[190:193], v[28:31]
	v_mfma_f32_16x16x32_bf16 v[24:27], v[182:185], v[190:193], v[24:27]
	v_mfma_f32_16x16x32_bf16 v[20:23], v[170:173], v[220:223], v[20:23]
	v_mfma_f32_16x16x32_bf16 v[16:19], v[182:185], v[220:223], v[16:19]
	v_mfma_f32_16x16x32_bf16 v[12:15], v[170:173], v[234:237], v[12:15]
	v_mfma_f32_16x16x32_bf16 v[8:11], v[182:185], v[234:237], v[8:11]
	v_mfma_f32_16x16x32_bf16 v[4:7], v[170:173], v[242:245], v[4:7]
	v_mfma_f32_16x16x32_bf16 v[0:3], v[182:185], v[242:245], v[0:3]
	s_setprio 0
	s_barrier
	s_add_i32 s26, 0, 0x1c000
	v_add_u32_e32 v162, s74, v175
	v_add_u32_e32 v177, s26, v175
	ds_read_b128 v[128:131], v162
	ds_read_b128 v[142:145], v162 offset:1024
	ds_read_b128 v[158:161], v162 offset:2048
	ds_read_b128 v[162:165], v162 offset:3072
	ds_read_b128 v[166:169], v177
	ds_read_b128 v[170:173], v177 offset:1024
	ds_read_b128 v[178:181], v177 offset:2048
	ds_read_b128 v[182:185], v177 offset:3072
	s_add_u32 s20, s30, s88
	s_addc_u32 s21, s31, 0
	s_mov_b32 m0, s82
	ds_read_b128 v[186:189], v176 offset:32768
	ds_read_b128 v[190:193], v176 offset:33792
	ds_read_b128 v[194:197], v176 offset:34816
	ds_read_b128 v[220:223], v176 offset:35840
	ds_read_b128 v[230:233], v176 offset:36864
	ds_read_b128 v[234:237], v176 offset:37888
	ds_read_b128 v[238:241], v176 offset:38912
	ds_read_b128 v[242:245], v176 offset:39936
	global_load_lds_dwordx4 v132, s[20:21]
	s_mov_b32 m0, s96
	s_nop 0
	global_load_lds_dwordx4 v134, s[20:21]
	s_waitcnt vmcnt(8)
	s_waitcnt lgkmcnt(0)
	s_barrier
	s_setprio 1
	s_waitcnt lgkmcnt(0)
	v_mfma_f32_16x16x32_bf16 v[124:127], v[128:131], v[186:189], v[124:127]
	v_mfma_f32_16x16x32_bf16 v[120:123], v[158:161], v[186:189], v[120:123]
	v_mfma_f32_16x16x32_bf16 v[116:119], v[128:131], v[194:197], v[116:119]
	v_mfma_f32_16x16x32_bf16 v[112:115], v[158:161], v[194:197], v[112:115]
	v_mfma_f32_16x16x32_bf16 v[108:111], v[128:131], v[230:233], v[108:111]
	v_mfma_f32_16x16x32_bf16 v[104:107], v[158:161], v[230:233], v[104:107]
	v_mfma_f32_16x16x32_bf16 v[100:103], v[128:131], v[238:241], v[100:103]
	v_mfma_f32_16x16x32_bf16 v[96:99], v[158:161], v[238:241], v[96:99]
	v_mfma_f32_16x16x32_bf16 v[124:127], v[142:145], v[190:193], v[124:127]
	v_mfma_f32_16x16x32_bf16 v[120:123], v[162:165], v[190:193], v[120:123]
	v_mfma_f32_16x16x32_bf16 v[116:119], v[142:145], v[220:223], v[116:119]
	v_mfma_f32_16x16x32_bf16 v[112:115], v[162:165], v[220:223], v[112:115]
	v_mfma_f32_16x16x32_bf16 v[108:111], v[142:145], v[234:237], v[108:111]
	v_mfma_f32_16x16x32_bf16 v[104:107], v[162:165], v[234:237], v[104:107]
	v_mfma_f32_16x16x32_bf16 v[100:103], v[142:145], v[242:245], v[100:103]
	v_mfma_f32_16x16x32_bf16 v[96:99], v[162:165], v[242:245], v[96:99]
	v_mfma_f32_16x16x32_bf16 v[60:63], v[166:169], v[186:189], v[60:63]
	v_mfma_f32_16x16x32_bf16 v[56:59], v[178:181], v[186:189], v[56:59]
	v_mfma_f32_16x16x32_bf16 v[52:55], v[166:169], v[194:197], v[52:55]
	v_mfma_f32_16x16x32_bf16 v[48:51], v[178:181], v[194:197], v[48:51]
	v_mfma_f32_16x16x32_bf16 v[44:47], v[166:169], v[230:233], v[44:47]
	v_mfma_f32_16x16x32_bf16 v[40:43], v[178:181], v[230:233], v[40:43]
	v_mfma_f32_16x16x32_bf16 v[36:39], v[166:169], v[238:241], v[36:39]
	v_mfma_f32_16x16x32_bf16 v[32:35], v[178:181], v[238:241], v[32:35]
	v_mfma_f32_16x16x32_bf16 v[60:63], v[170:173], v[190:193], v[60:63]
	v_mfma_f32_16x16x32_bf16 v[56:59], v[182:185], v[190:193], v[56:59]
	v_mfma_f32_16x16x32_bf16 v[52:55], v[170:173], v[220:223], v[52:55]
	v_mfma_f32_16x16x32_bf16 v[48:51], v[182:185], v[220:223], v[48:51]
	v_mfma_f32_16x16x32_bf16 v[44:47], v[170:173], v[234:237], v[44:47]
	v_mfma_f32_16x16x32_bf16 v[40:43], v[182:185], v[234:237], v[40:43]
	v_mfma_f32_16x16x32_bf16 v[36:39], v[170:173], v[242:245], v[36:39]
	v_mfma_f32_16x16x32_bf16 v[32:35], v[182:185], v[242:245], v[32:35]
	s_setprio 0
	s_barrier
; #define PG8_STAGE(bufoff, gbase, voff) do { _Pragma("unroll") for (int _i = 0; _i < 2; ++_i) \
;         __builtin_amdgcn_global_load_lds((const unsigned*)((const char*)(gbase) + (voff)[_i]), (LAS unsigned*)(lds + (bufoff) + ldsw + _i * 8192), 16, 0, 0); } while (0)
; #define PG8_LDA(dst, b, h) do { _Pragma("unroll") for (int m = 0; m < 4; ++m) _Pragma("unroll") for (int k = 0; k < 2; ++k) dst[m][k] = *(const LAS bf16x8*)(lds + PG8_SA(b, h) + aoff + m * 2048 + k * 1024); } while (0)
; #define PG8_MMA(ai, bj, At, Bt) do { __builtin_amdgcn_s_setprio(1); _Pragma("unroll") for (int m = 0; m < 4; ++m) _Pragma("unroll") for (int n = 0; n < 2; ++n) _Pragma("unroll") for (int k = 0; k < 2; ++k) \
;         acc[ai][bj][m][n] = __builtin_amdgcn_mfma_f32_16x16x32_bf16(Bt[n][k], At[m][k], acc[ai][bj][m][n], 0, 0, 0); __builtin_amdgcn_s_setprio(0); } while (0)
; #define PG8_WAIT_V(n) asm volatile("s_waitcnt vmcnt(" #n ")" ::: "memory")
; #define PG8_WAIT_L(n) asm volatile("s_waitcnt lgkmcnt(" #n ")" ::: "memory")
; #define PG8_BAR __builtin_amdgcn_s_barrier()
; #define PG8_SCHED __builtin_amdgcn_sched_barrier(0)
; template <class Epi>
; DI void gemm_phase(LAS unsigned char* lds, const Gemm g, const StaticOrder S, const Epi E) {
;     ...
;             PG8_LDA(At, 1, 1); PG8_STAGE(PG8_SB(1, 0), b3, voffB); PG8_STAGE(PG8_SB(1, 1), b3 + hstepB, voffB); PG8_STAGE(PG8_SA(1, 0), a3, voffA);
;             PG8_WAIT_V(8); PG8_WAIT_L(0); PG8_BAR; PG8_MMA(1, 0, At, B0); PG8_MMA(1, 1, At, B1); PG8_BAR; PG8_SCHED;
;         }
;         if (wr == 0) PG8_BAR;
	s_add_i32 s20, s74, s81
	s_mov_b32 m0, s20
	ds_read_b128 v[186:189], v176 offset:49152
	ds_read_b128 v[190:193], v176 offset:50176
	ds_read_b128 v[194:197], v176 offset:51200
	ds_read_b128 v[220:223], v176 offset:52224
	ds_read_b128 v[230:233], v176 offset:53248
	ds_read_b128 v[234:237], v176 offset:54272
	ds_read_b128 v[238:241], v176 offset:55296
	ds_read_b128 v[242:245], v176 offset:56320
	global_load_lds_dwordx4 v146, s[98:99]
	s_add_i32 m0, s20, 0x2000
	s_add_i32 s20, s26, s81
	global_load_lds_dwordx4 v136, s[98:99]
	s_mov_b32 m0, s20
	s_nop 0
	global_load_lds_dwordx4 v146, s[100:101]
	s_add_i32 m0, s20, 0x2000
	s_nop 0
	global_load_lds_dwordx4 v136, s[100:101]
	s_mov_b32 m0, s86
	s_nop 0
	s_add_u32 s98, s30, 0x80
	s_addc_u32 s99, s31, 0
	global_load_lds_dwordx4 v132, s[98:99]
	s_mov_b32 m0, s87
	s_nop 0
	global_load_lds_dwordx4 v134, s[98:99]
	s_waitcnt vmcnt(8)
	s_waitcnt lgkmcnt(0)
	s_barrier
	s_setprio 1
	s_waitcnt lgkmcnt(0)
	v_mfma_f32_16x16x32_bf16 v[92:95], v[128:131], v[186:189], v[92:95]
	v_mfma_f32_16x16x32_bf16 v[88:91], v[158:161], v[186:189], v[88:91]
	v_mfma_f32_16x16x32_bf16 v[84:87], v[128:131], v[194:197], v[84:87]
	v_mfma_f32_16x16x32_bf16 v[80:83], v[158:161], v[194:197], v[80:83]
	v_mfma_f32_16x16x32_bf16 v[76:79], v[128:131], v[230:233], v[76:79]
	v_mfma_f32_16x16x32_bf16 v[72:75], v[158:161], v[230:233], v[72:75]
	v_mfma_f32_16x16x32_bf16 v[68:71], v[128:131], v[238:241], v[68:71]
	v_mfma_f32_16x16x32_bf16 v[64:67], v[158:161], v[238:241], v[64:67]
	v_mfma_f32_16x16x32_bf16 v[92:95], v[142:145], v[190:193], v[92:95]
	v_mfma_f32_16x16x32_bf16 v[88:91], v[162:165], v[190:193], v[88:91]
	v_mfma_f32_16x16x32_bf16 v[84:87], v[142:145], v[220:223], v[84:87]
	v_mfma_f32_16x16x32_bf16 v[80:83], v[162:165], v[220:223], v[80:83]
	v_mfma_f32_16x16x32_bf16 v[76:79], v[142:145], v[234:237], v[76:79]
	v_mfma_f32_16x16x32_bf16 v[72:75], v[162:165], v[234:237], v[72:75]
	v_mfma_f32_16x16x32_bf16 v[68:71], v[142:145], v[242:245], v[68:71]
	v_mfma_f32_16x16x32_bf16 v[64:67], v[162:165], v[242:245], v[64:67]
	v_mfma_f32_16x16x32_bf16 v[28:31], v[166:169], v[186:189], v[28:31]
	v_mfma_f32_16x16x32_bf16 v[24:27], v[178:181], v[186:189], v[24:27]
	v_mfma_f32_16x16x32_bf16 v[20:23], v[166:169], v[194:197], v[20:23]
	v_mfma_f32_16x16x32_bf16 v[16:19], v[178:181], v[194:197], v[16:19]
	v_mfma_f32_16x16x32_bf16 v[12:15], v[166:169], v[230:233], v[12:15]
	v_mfma_f32_16x16x32_bf16 v[8:11], v[178:181], v[230:233], v[8:11]
	v_mfma_f32_16x16x32_bf16 v[4:7], v[166:169], v[238:241], v[4:7]
	v_mfma_f32_16x16x32_bf16 v[0:3], v[178:181], v[238:241], v[0:3]
	v_mfma_f32_16x16x32_bf16 v[28:31], v[170:173], v[190:193], v[28:31]
	v_mfma_f32_16x16x32_bf16 v[24:27], v[182:185], v[190:193], v[24:27]
	v_mfma_f32_16x16x32_bf16 v[20:23], v[170:173], v[220:223], v[20:23]
	v_mfma_f32_16x16x32_bf16 v[16:19], v[182:185], v[220:223], v[16:19]
	v_mfma_f32_16x16x32_bf16 v[12:15], v[170:173], v[234:237], v[12:15]
	v_mfma_f32_16x16x32_bf16 v[8:11], v[182:185], v[234:237], v[8:11]
	v_mfma_f32_16x16x32_bf16 v[4:7], v[170:173], v[242:245], v[4:7]
	v_mfma_f32_16x16x32_bf16 v[0:3], v[182:185], v[242:245], v[0:3]
	s_setprio 0
	s_barrier
	s_add_u32 s42, s42, 0x100
	s_addc_u32 s43, s43, 0
	s_add_u32 s44, s44, 0x100
	s_addc_u32 s45, s45, 0
	s_cmp_ge_i32 vcc_lo, s2
	s_mov_b32 s30, vcc_lo
	s_cbranch_scc0 .LBB0_430
	s_and_b64 vcc, exec, s[60:61]
	s_cbranch_vccz .LBB0_433
	s_barrier

; #define PG8_STAGE(bufoff, gbase, voff) do { _Pragma("unroll") for (int _i = 0; _i < 2; ++_i) \
;         __builtin_amdgcn_global_load_lds((const unsigned*)((const char*)(gbase) + (voff)[_i]), (LAS unsigned*)(lds + (bufoff) + ldsw + _i * 8192), 16, 0, 0); } while (0)
; #define PG8_LDA(dst, b, h) do { _Pragma("unroll") for (int m = 0; m < 4; ++m) _Pragma("unroll") for (int k = 0; k < 2; ++k) dst[m][k] = *(const LAS bf16x8*)(lds + PG8_SA(b, h) + aoff + m * 2048 + k * 1024); } while (0)
; #define PG8_LDB(dst, b, h) do { _Pragma("unroll") for (int n = 0; n < 2; ++n) _Pragma("unroll") for (int k = 0; k < 2; ++k) dst[n][k] = *(const LAS bf16x8*)(lds + PG8_SB(b, h) + boff + n * 2048 + k * 1024); } while (0)
; #define PG8_MMA(ai, bj, At, Bt) do { __builtin_amdgcn_s_setprio(1); _Pragma("unroll") for (int m = 0; m < 4; ++m) _Pragma("unroll") for (int n = 0; n < 2; ++n) _Pragma("unroll") for (int k = 0; k < 2; ++k) \
;         acc[ai][bj][m][n] = __builtin_amdgcn_mfma_f32_16x16x32_bf16(Bt[n][k], At[m][k], acc[ai][bj][m][n], 0, 0, 0); __builtin_amdgcn_s_setprio(0); } while (0)
; #define PG8_WAIT_V(n) asm volatile("s_waitcnt vmcnt(" #n ")" ::: "memory")
; #define PG8_WAIT_L(n) asm volatile("s_waitcnt lgkmcnt(" #n ")" ::: "memory")
; #define PG8_BAR __builtin_amdgcn_s_barrier()
; #define PG8_SCHED __builtin_amdgcn_sched_barrier(0)
; template <class Epi>
; DI void gemm_phase(LAS unsigned char* lds, const Gemm g, const StaticOrder S, const Epi E) {
;     ...
;         for (int t = 0; t < nt; t += 2) {
;             const bool last = (t == nt - 2);
;             const char* a1 = cA + (size_t)(t + 1) * kstep;
;             const char* a2 = last ? nA : cA + (size_t)(t + 2) * kstep; const char* b2 = last ? nB : cB + (size_t)(t + 2) * kstep;
;             const char* a3 = a2 + kstep; const char* b3 = b2 + kstep;
;             PG8_LDB(B0, 0, 0); PG8_LDB(B1, 0, 1); PG8_SCHED; PG8_LDA(At, 0, 0); PG8_STAGE(PG8_SA(1, 1), a1 + hstepA, voffA);
;             PG8_WAIT_V(8); PG8_WAIT_L(0); PG8_BAR; PG8_MMA(0, 0, At, B0); PG8_MMA(0, 1, At, B1); PG8_BAR; PG8_SCHED;
;             PG8_LDA(At, 0, 1); PG8_STAGE(PG8_SB(0, 0), b2, voffB); PG8_STAGE(PG8_SB(0, 1), b2 + hstepB, voffB); PG8_STAGE(PG8_SA(0, 0), a2, voffA);
;             PG8_WAIT_V(8); PG8_WAIT_L(0); PG8_BAR; PG8_MMA(1, 0, At, B0); PG8_MMA(1, 1, At, B1); PG8_BAR; PG8_SCHED;
.LBB0_471:
	s_add_u32 s20, s52, 0xfffc0080
	s_addc_u32 s21, s53, -1
	s_add_i32 s70, 0, 0x10000
	s_cmp_eq_u32 s69, 12
	s_cselect_b32 s55, s47, s21
	s_cselect_b32 s54, s46, s20
	v_add_u32_e32 v138, s70, v142
	s_cselect_b32 s31, s49, s45
	s_cselect_b32 s30, s48, s43
	s_add_i32 s20, 0, 0x14000
	ds_read_b128 v[158:161], v138
	ds_read_b128 v[162:165], v138 offset:1024
	ds_read_b128 v[166:169], v138 offset:2048
	ds_read_b128 v[170:173], v138 offset:3072
	v_add_u32_e32 v138, s20, v142
	ds_read_b128 v[174:177], v138
	ds_read_b128 v[178:181], v138 offset:1024
	ds_read_b128 v[182:185], v138 offset:2048
	ds_read_b128 v[186:189], v138 offset:3072
	s_add_i32 m0, s51, 0xc000
	ds_read_b128 v[190:193], v143
	ds_read_b128 v[194:197], v143 offset:1024
	ds_read_b128 v[220:223], v143 offset:2048
	ds_read_b128 v[230:233], v143 offset:3072
	ds_read_b128 v[234:237], v143 offset:4096
	ds_read_b128 v[238:241], v143 offset:5120
	ds_read_b128 v[242:245], v143 offset:6144
	ds_read_b128 v[246:249], v143 offset:7168
	global_load_lds_dwordx4 v134, s[52:53]
	s_add_i32 m0, s51, 0xe000
	s_nop 0
	global_load_lds_dwordx4 v136, s[52:53]
	s_waitcnt vmcnt(8)
	s_waitcnt lgkmcnt(0)
	s_barrier
	s_setprio 1
	s_waitcnt lgkmcnt(0)
	v_mfma_f32_16x16x32_bf16 v[124:127], v[158:161], v[190:193], v[124:127]
	v_mfma_f32_16x16x32_bf16 v[120:123], v[166:169], v[190:193], v[120:123]
	v_mfma_f32_16x16x32_bf16 v[108:111], v[158:161], v[220:223], v[108:111]
	v_mfma_f32_16x16x32_bf16 v[100:103], v[166:169], v[220:223], v[100:103]
	v_mfma_f32_16x16x32_bf16 v[92:95], v[158:161], v[234:237], v[92:95]
	v_mfma_f32_16x16x32_bf16 v[84:87], v[166:169], v[234:237], v[84:87]
	v_mfma_f32_16x16x32_bf16 v[76:79], v[158:161], v[242:245], v[76:79]
	v_mfma_f32_16x16x32_bf16 v[68:71], v[166:169], v[242:245], v[68:71]
	v_mfma_f32_16x16x32_bf16 v[124:127], v[162:165], v[194:197], v[124:127]
	v_mfma_f32_16x16x32_bf16 v[120:123], v[170:173], v[194:197], v[120:123]
	v_mfma_f32_16x16x32_bf16 v[108:111], v[162:165], v[230:233], v[108:111]
	v_mfma_f32_16x16x32_bf16 v[100:103], v[170:173], v[230:233], v[100:103]
	v_mfma_f32_16x16x32_bf16 v[92:95], v[162:165], v[238:241], v[92:95]
	v_mfma_f32_16x16x32_bf16 v[84:87], v[170:173], v[238:241], v[84:87]
	v_mfma_f32_16x16x32_bf16 v[76:79], v[162:165], v[246:249], v[76:79]
	v_mfma_f32_16x16x32_bf16 v[68:71], v[170:173], v[246:249], v[68:71]
	v_mfma_f32_16x16x32_bf16 v[116:119], v[174:177], v[190:193], v[116:119]
	v_mfma_f32_16x16x32_bf16 v[112:115], v[182:185], v[190:193], v[112:115]
	v_mfma_f32_16x16x32_bf16 v[104:107], v[174:177], v[220:223], v[104:107]
	v_mfma_f32_16x16x32_bf16 v[96:99], v[182:185], v[220:223], v[96:99]
	v_mfma_f32_16x16x32_bf16 v[88:91], v[174:177], v[234:237], v[88:91]
	v_mfma_f32_16x16x32_bf16 v[80:83], v[182:185], v[234:237], v[80:83]
	v_mfma_f32_16x16x32_bf16 v[72:75], v[174:177], v[242:245], v[72:75]
	v_mfma_f32_16x16x32_bf16 v[64:67], v[182:185], v[242:245], v[64:67]
	v_mfma_f32_16x16x32_bf16 v[116:119], v[178:181], v[194:197], v[116:119]
	v_mfma_f32_16x16x32_bf16 v[112:115], v[186:189], v[194:197], v[112:115]
	v_mfma_f32_16x16x32_bf16 v[104:107], v[178:181], v[230:233], v[104:107]
	v_mfma_f32_16x16x32_bf16 v[96:99], v[186:189], v[230:233], v[96:99]
	v_mfma_f32_16x16x32_bf16 v[88:91], v[178:181], v[238:241], v[88:91]
	v_mfma_f32_16x16x32_bf16 v[80:83], v[186:189], v[238:241], v[80:83]
	v_mfma_f32_16x16x32_bf16 v[72:75], v[178:181], v[246:249], v[72:75]
	v_mfma_f32_16x16x32_bf16 v[64:67], v[186:189], v[246:249], v[64:67]
	s_setprio 0
	s_barrier
	s_add_i32 s21, s70, s57
	s_mov_b32 m0, s21
	ds_read_b128 v[190:193], v143 offset:16384
	ds_read_b128 v[194:197], v143 offset:17408
	ds_read_b128 v[220:223], v143 offset:18432
	ds_read_b128 v[230:233], v143 offset:19456
	ds_read_b128 v[234:237], v143 offset:20480
	ds_read_b128 v[238:241], v143 offset:21504
	ds_read_b128 v[242:245], v143 offset:22528
	ds_read_b128 v[246:249], v143 offset:23552
	global_load_lds_dwordx4 v146, s[30:31]
	s_add_i32 m0, s21, 0x2000
	s_add_u32 s70, s30, 0x40000
	s_addc_u32 s71, s31, 0
	s_add_i32 s20, s20, s57
	global_load_lds_dwordx4 v128, s[30:31]
	s_mov_b32 m0, s20
	s_add_u32 s98, s30, 0x80
	s_addc_u32 s99, s31, 0
	global_load_lds_dwordx4 v146, s[70:71]
	s_add_i32 m0, s20, 0x2000
	s_add_u32 s100, s54, 0x80
	global_load_lds_dwordx4 v128, s[70:71]
	s_mov_b32 m0, s51
	s_addc_u32 s101, s55, 0
	global_load_lds_dwordx4 v132, s[54:55]
	s_mov_b32 m0, s61
	s_nop 0
	global_load_lds_dwordx4 v130, s[54:55]
	s_waitcnt vmcnt(8)
	s_waitcnt lgkmcnt(0)
	s_barrier
	s_setprio 1
	s_waitcnt lgkmcnt(0)
	v_mfma_f32_16x16x32_bf16 v[60:63], v[158:161], v[190:193], v[60:63]
	v_mfma_f32_16x16x32_bf16 v[52:55], v[166:169], v[190:193], v[52:55]
	v_mfma_f32_16x16x32_bf16 v[44:47], v[158:161], v[220:223], v[44:47]
	v_mfma_f32_16x16x32_bf16 v[36:39], v[166:169], v[220:223], v[36:39]
	v_mfma_f32_16x16x32_bf16 v[28:31], v[158:161], v[234:237], v[28:31]
	v_mfma_f32_16x16x32_bf16 v[20:23], v[166:169], v[234:237], v[20:23]
	v_mfma_f32_16x16x32_bf16 v[12:15], v[158:161], v[242:245], v[12:15]
	v_mfma_f32_16x16x32_bf16 v[4:7], v[166:169], v[242:245], v[4:7]
	v_mfma_f32_16x16x32_bf16 v[60:63], v[162:165], v[194:197], v[60:63]
	v_mfma_f32_16x16x32_bf16 v[52:55], v[170:173], v[194:197], v[52:55]
	v_mfma_f32_16x16x32_bf16 v[44:47], v[162:165], v[230:233], v[44:47]
	v_mfma_f32_16x16x32_bf16 v[36:39], v[170:173], v[230:233], v[36:39]
	v_mfma_f32_16x16x32_bf16 v[28:31], v[162:165], v[238:241], v[28:31]
	v_mfma_f32_16x16x32_bf16 v[20:23], v[170:173], v[238:241], v[20:23]
	v_mfma_f32_16x16x32_bf16 v[12:15], v[162:165], v[246:249], v[12:15]
	v_mfma_f32_16x16x32_bf16 v[4:7], v[170:173], v[246:249], v[4:7]
	v_mfma_f32_16x16x32_bf16 v[56:59], v[174:177], v[190:193], v[56:59]
	v_mfma_f32_16x16x32_bf16 v[48:51], v[182:185], v[190:193], v[48:51]
	v_mfma_f32_16x16x32_bf16 v[40:43], v[174:177], v[220:223], v[40:43]
	v_mfma_f32_16x16x32_bf16 v[32:35], v[182:185], v[220:223], v[32:35]
	v_mfma_f32_16x16x32_bf16 v[24:27], v[174:177], v[234:237], v[24:27]
	v_mfma_f32_16x16x32_bf16 v[16:19], v[182:185], v[234:237], v[16:19]
	v_mfma_f32_16x16x32_bf16 v[8:11], v[174:177], v[242:245], v[8:11]
	v_mfma_f32_16x16x32_bf16 v[0:3], v[182:185], v[242:245], v[0:3]
	v_mfma_f32_16x16x32_bf16 v[56:59], v[178:181], v[194:197], v[56:59]
	v_mfma_f32_16x16x32_bf16 v[48:51], v[186:189], v[194:197], v[48:51]
	v_mfma_f32_16x16x32_bf16 v[40:43], v[178:181], v[230:233], v[40:43]
	v_mfma_f32_16x16x32_bf16 v[32:35], v[186:189], v[230:233], v[32:35]
	v_mfma_f32_16x16x32_bf16 v[24:27], v[178:181], v[238:241], v[24:27]
	v_mfma_f32_16x16x32_bf16 v[16:19], v[186:189], v[238:241], v[16:19]
	v_mfma_f32_16x16x32_bf16 v[8:11], v[178:181], v[246:249], v[8:11]
	v_mfma_f32_16x16x32_bf16 v[0:3], v[186:189], v[246:249], v[0:3]
	s_setprio 0
	s_barrier
; #define PG8_STAGE(bufoff, gbase, voff) do { _Pragma("unroll") for (int _i = 0; _i < 2; ++_i) \
;         __builtin_amdgcn_global_load_lds((const unsigned*)((const char*)(gbase) + (voff)[_i]), (LAS unsigned*)(lds + (bufoff) + ldsw + _i * 8192), 16, 0, 0); } while (0)
; #define PG8_LDA(dst, b, h) do { _Pragma("unroll") for (int m = 0; m < 4; ++m) _Pragma("unroll") for (int k = 0; k < 2; ++k) dst[m][k] = *(const LAS bf16x8*)(lds + PG8_SA(b, h) + aoff + m * 2048 + k * 1024); } while (0)
; #define PG8_LDB(dst, b, h) do { _Pragma("unroll") for (int n = 0; n < 2; ++n) _Pragma("unroll") for (int k = 0; k < 2; ++k) dst[n][k] = *(const LAS bf16x8*)(lds + PG8_SB(b, h) + boff + n * 2048 + k * 1024); } while (0)
; #define PG8_MMA(ai, bj, At, Bt) do { __builtin_amdgcn_s_setprio(1); _Pragma("unroll") for (int m = 0; m < 4; ++m) _Pragma("unroll") for (int n = 0; n < 2; ++n) _Pragma("unroll") for (int k = 0; k < 2; ++k) \
;         acc[ai][bj][m][n] = __builtin_amdgcn_mfma_f32_16x16x32_bf16(Bt[n][k], At[m][k], acc[ai][bj][m][n], 0, 0, 0); __builtin_amdgcn_s_setprio(0); } while (0)
; #define PG8_WAIT_V(n) asm volatile("s_waitcnt vmcnt(" #n ")" ::: "memory")
; #define PG8_WAIT_L(n) asm volatile("s_waitcnt lgkmcnt(" #n ")" ::: "memory")
; #define PG8_BAR __builtin_amdgcn_s_barrier()
; #define PG8_SCHED __builtin_amdgcn_sched_barrier(0)
; template <class Epi>
; DI void gemm_phase(LAS unsigned char* lds, const Gemm g, const StaticOrder S, const Epi E) {
;     ...
;             PG8_LDB(B0, 1, 0); PG8_LDB(B1, 1, 1); PG8_SCHED; PG8_LDA(At, 1, 0); PG8_STAGE(PG8_SA(0, 1), a2 + hstepA, voffA);
;             PG8_WAIT_V(8); PG8_WAIT_L(0); PG8_BAR; PG8_MMA(0, 0, At, B0); PG8_MMA(0, 1, At, B1); PG8_BAR; PG8_SCHED;
;             PG8_LDA(At, 1, 1); PG8_STAGE(PG8_SB(1, 0), b3, voffB); PG8_STAGE(PG8_SB(1, 1), b3 + hstepB, voffB); PG8_STAGE(PG8_SA(1, 0), a3, voffA);
;             PG8_WAIT_V(8); PG8_WAIT_L(0); PG8_BAR; PG8_MMA(1, 0, At, B0); PG8_MMA(1, 1, At, B1); PG8_BAR; PG8_SCHED;
;         }
;         if (wr == 0) PG8_BAR;
	v_add_u32_e32 v157, s74, v142
	s_add_i32 s20, 0, 0x1c000
	ds_read_b128 v[158:161], v157
	ds_read_b128 v[162:165], v157 offset:1024
	ds_read_b128 v[166:169], v157 offset:2048
	ds_read_b128 v[170:173], v157 offset:3072
	v_add_u32_e32 v157, s20, v142
	ds_read_b128 v[174:177], v157
	ds_read_b128 v[178:181], v157 offset:1024
	ds_read_b128 v[182:185], v157 offset:2048
	ds_read_b128 v[186:189], v157 offset:3072
	s_add_u32 s54, s54, 0x40000
	s_addc_u32 s55, s55, 0
	s_mov_b32 m0, s62
	ds_read_b128 v[190:193], v143 offset:32768
	ds_read_b128 v[194:197], v143 offset:33792
	ds_read_b128 v[220:223], v143 offset:34816
	ds_read_b128 v[230:233], v143 offset:35840
	ds_read_b128 v[234:237], v143 offset:36864
	ds_read_b128 v[238:241], v143 offset:37888
	ds_read_b128 v[242:245], v143 offset:38912
	ds_read_b128 v[246:249], v143 offset:39936
	global_load_lds_dwordx4 v132, s[54:55]
	s_mov_b32 m0, s63
	s_nop 0
	global_load_lds_dwordx4 v130, s[54:55]
	s_waitcnt vmcnt(8)
	s_waitcnt lgkmcnt(0)
	s_barrier
	s_setprio 1
	s_waitcnt lgkmcnt(0)
	v_mfma_f32_16x16x32_bf16 v[124:127], v[158:161], v[190:193], v[124:127]
	v_mfma_f32_16x16x32_bf16 v[120:123], v[166:169], v[190:193], v[120:123]
	v_mfma_f32_16x16x32_bf16 v[108:111], v[158:161], v[220:223], v[108:111]
	v_mfma_f32_16x16x32_bf16 v[100:103], v[166:169], v[220:223], v[100:103]
	v_mfma_f32_16x16x32_bf16 v[92:95], v[158:161], v[234:237], v[92:95]
	v_mfma_f32_16x16x32_bf16 v[84:87], v[166:169], v[234:237], v[84:87]
	v_mfma_f32_16x16x32_bf16 v[76:79], v[158:161], v[242:245], v[76:79]
	v_mfma_f32_16x16x32_bf16 v[68:71], v[166:169], v[242:245], v[68:71]
	v_mfma_f32_16x16x32_bf16 v[124:127], v[162:165], v[194:197], v[124:127]
	v_mfma_f32_16x16x32_bf16 v[120:123], v[170:173], v[194:197], v[120:123]
	v_mfma_f32_16x16x32_bf16 v[108:111], v[162:165], v[230:233], v[108:111]
	v_mfma_f32_16x16x32_bf16 v[100:103], v[170:173], v[230:233], v[100:103]
	v_mfma_f32_16x16x32_bf16 v[92:95], v[162:165], v[238:241], v[92:95]
	v_mfma_f32_16x16x32_bf16 v[84:87], v[170:173], v[238:241], v[84:87]
	v_mfma_f32_16x16x32_bf16 v[76:79], v[162:165], v[246:249], v[76:79]
	v_mfma_f32_16x16x32_bf16 v[68:71], v[170:173], v[246:249], v[68:71]
	v_mfma_f32_16x16x32_bf16 v[116:119], v[174:177], v[190:193], v[116:119]
	v_mfma_f32_16x16x32_bf16 v[112:115], v[182:185], v[190:193], v[112:115]
	v_mfma_f32_16x16x32_bf16 v[104:107], v[174:177], v[220:223], v[104:107]
	v_mfma_f32_16x16x32_bf16 v[96:99], v[182:185], v[220:223], v[96:99]
	v_mfma_f32_16x16x32_bf16 v[88:91], v[174:177], v[234:237], v[88:91]
	v_mfma_f32_16x16x32_bf16 v[80:83], v[182:185], v[234:237], v[80:83]
	v_mfma_f32_16x16x32_bf16 v[72:75], v[174:177], v[242:245], v[72:75]
	v_mfma_f32_16x16x32_bf16 v[64:67], v[182:185], v[242:245], v[64:67]
	v_mfma_f32_16x16x32_bf16 v[116:119], v[178:181], v[194:197], v[116:119]
	v_mfma_f32_16x16x32_bf16 v[112:115], v[186:189], v[194:197], v[112:115]
	v_mfma_f32_16x16x32_bf16 v[104:107], v[178:181], v[230:233], v[104:107]
	v_mfma_f32_16x16x32_bf16 v[96:99], v[186:189], v[230:233], v[96:99]
	v_mfma_f32_16x16x32_bf16 v[88:91], v[178:181], v[238:241], v[88:91]
	v_mfma_f32_16x16x32_bf16 v[80:83], v[186:189], v[238:241], v[80:83]
	v_mfma_f32_16x16x32_bf16 v[72:75], v[178:181], v[246:249], v[72:75]
	v_mfma_f32_16x16x32_bf16 v[64:67], v[186:189], v[246:249], v[64:67]
	s_setprio 0
	s_barrier
	s_add_i32 s21, s74, s57
	s_mov_b32 m0, s21
	ds_read_b128 v[190:193], v143 offset:49152
	ds_read_b128 v[194:197], v143 offset:50176
	ds_read_b128 v[220:223], v143 offset:51200
	ds_read_b128 v[230:233], v143 offset:52224
	ds_read_b128 v[234:237], v143 offset:53248
	ds_read_b128 v[238:241], v143 offset:54272
	ds_read_b128 v[242:245], v143 offset:55296
	ds_read_b128 v[246:249], v143 offset:56320
	global_load_lds_dwordx4 v146, s[98:99]
	s_add_i32 m0, s21, 0x2000
	s_add_u32 s30, s30, 0x40080
	s_addc_u32 s31, s31, 0
	s_add_i32 s20, s20, s57
	global_load_lds_dwordx4 v128, s[98:99]
	s_mov_b32 m0, s20
	s_nop 0
	global_load_lds_dwordx4 v146, s[30:31]
	s_add_i32 m0, s20, 0x2000
	s_nop 0
	global_load_lds_dwordx4 v128, s[30:31]
	s_mov_b32 m0, s66
	s_nop 0
	global_load_lds_dwordx4 v132, s[100:101]
	s_mov_b32 m0, s67
	s_nop 0
	global_load_lds_dwordx4 v130, s[100:101]
	s_waitcnt vmcnt(8)
	s_waitcnt lgkmcnt(0)
	s_barrier
	s_setprio 1
	s_waitcnt lgkmcnt(0)
	v_mfma_f32_16x16x32_bf16 v[60:63], v[158:161], v[190:193], v[60:63]
	v_mfma_f32_16x16x32_bf16 v[52:55], v[166:169], v[190:193], v[52:55]
	v_mfma_f32_16x16x32_bf16 v[44:47], v[158:161], v[220:223], v[44:47]
	v_mfma_f32_16x16x32_bf16 v[36:39], v[166:169], v[220:223], v[36:39]
	v_mfma_f32_16x16x32_bf16 v[28:31], v[158:161], v[234:237], v[28:31]
	v_mfma_f32_16x16x32_bf16 v[20:23], v[166:169], v[234:237], v[20:23]
	v_mfma_f32_16x16x32_bf16 v[12:15], v[158:161], v[242:245], v[12:15]
	v_mfma_f32_16x16x32_bf16 v[4:7], v[166:169], v[242:245], v[4:7]
	v_mfma_f32_16x16x32_bf16 v[60:63], v[162:165], v[194:197], v[60:63]
	v_mfma_f32_16x16x32_bf16 v[52:55], v[170:173], v[194:197], v[52:55]
	v_mfma_f32_16x16x32_bf16 v[44:47], v[162:165], v[230:233], v[44:47]
	v_mfma_f32_16x16x32_bf16 v[36:39], v[170:173], v[230:233], v[36:39]
	v_mfma_f32_16x16x32_bf16 v[28:31], v[162:165], v[238:241], v[28:31]
	v_mfma_f32_16x16x32_bf16 v[20:23], v[170:173], v[238:241], v[20:23]
	v_mfma_f32_16x16x32_bf16 v[12:15], v[162:165], v[246:249], v[12:15]
	v_mfma_f32_16x16x32_bf16 v[4:7], v[170:173], v[246:249], v[4:7]
	v_mfma_f32_16x16x32_bf16 v[56:59], v[174:177], v[190:193], v[56:59]
	v_mfma_f32_16x16x32_bf16 v[48:51], v[182:185], v[190:193], v[48:51]
	v_mfma_f32_16x16x32_bf16 v[40:43], v[174:177], v[220:223], v[40:43]
	v_mfma_f32_16x16x32_bf16 v[32:35], v[182:185], v[220:223], v[32:35]
	v_mfma_f32_16x16x32_bf16 v[24:27], v[174:177], v[234:237], v[24:27]
	v_mfma_f32_16x16x32_bf16 v[16:19], v[182:185], v[234:237], v[16:19]
	v_mfma_f32_16x16x32_bf16 v[8:11], v[174:177], v[242:245], v[8:11]
	v_mfma_f32_16x16x32_bf16 v[0:3], v[182:185], v[242:245], v[0:3]
	v_mfma_f32_16x16x32_bf16 v[56:59], v[178:181], v[194:197], v[56:59]
	v_mfma_f32_16x16x32_bf16 v[48:51], v[186:189], v[194:197], v[48:51]
	v_mfma_f32_16x16x32_bf16 v[40:43], v[178:181], v[230:233], v[40:43]
	v_mfma_f32_16x16x32_bf16 v[32:35], v[186:189], v[230:233], v[32:35]
	v_mfma_f32_16x16x32_bf16 v[24:27], v[178:181], v[238:241], v[24:27]
	v_mfma_f32_16x16x32_bf16 v[16:19], v[186:189], v[238:241], v[16:19]
	v_mfma_f32_16x16x32_bf16 v[8:11], v[178:181], v[246:249], v[8:11]
	v_mfma_f32_16x16x32_bf16 v[0:3], v[186:189], v[246:249], v[0:3]
	s_setprio 0
	s_barrier
	s_add_i32 s69, s69, 2
	s_add_u32 s52, s52, 0x100
	s_addc_u32 s53, s53, 0
	s_add_u32 s43, s43, 0x100
	s_addc_u32 s45, s45, 0
	s_cmp_gt_u32 s69, 13
	s_cbranch_scc0 .LBB0_471
	s_and_b64 vcc, exec, s[22:23]
	s_cbranch_vccz .LBB0_474
	s_barrier
